# GEMM main loops: per-segment s_setprio flips deleted, one static s_setprio 1 for waves 4-7 before each loop (reset after it)
# speedup vs baseline: 1.0113x; 1.0032x over previous
; template <class Epi>
; __device__ __forceinline__ void gemm_phase(LAS unsigned char* lds, const Gemm g, const StaticOrder& S, const Epi& E) {
;     ...
; #pragma unroll
;         for (int a = 0; a < 2; ++a)
; #pragma unroll
;             for (int b = 0; b < 2; ++b)
; #pragma unroll
;                 for (int m = 0; m < 4; ++m)
; #pragma unroll
;                     for (int n = 0; n < 2; ++n) acc[a][b][m][n] = (f32x4){0.f, 0.f, 0.f, 0.f};
;         cur = nxt; cA = nA; cB = nB; ++ui;
.LBB0_117:
	v_mov_b32_e32 v127, 0
	s_andn2_b64 vcc, exec, s[6:7]
	v_mov_b32_e32 v126, v127
	v_mov_b32_e32 v125, v127
	v_mov_b32_e32 v124, v127
	v_mov_b32_e32 v123, v127
	v_mov_b32_e32 v122, v127
	v_mov_b32_e32 v121, v127
	v_mov_b32_e32 v120, v127
	v_mov_b32_e32 v111, v127
	v_mov_b32_e32 v110, v127
	v_mov_b32_e32 v109, v127
	v_mov_b32_e32 v108, v127
	v_mov_b32_e32 v107, v127
	v_mov_b32_e32 v106, v127
	v_mov_b32_e32 v105, v127
	v_mov_b32_e32 v104, v127
	v_mov_b32_e32 v95, v127
	v_mov_b32_e32 v94, v127
	v_mov_b32_e32 v93, v127
	v_mov_b32_e32 v92, v127
	v_mov_b32_e32 v91, v127
	v_mov_b32_e32 v90, v127
	v_mov_b32_e32 v89, v127
	v_mov_b32_e32 v88, v127
	v_mov_b32_e32 v79, v127
	v_mov_b32_e32 v78, v127
	v_mov_b32_e32 v77, v127
	v_mov_b32_e32 v76, v127
	v_mov_b32_e32 v75, v127
	v_mov_b32_e32 v74, v127
	v_mov_b32_e32 v73, v127
	v_mov_b32_e32 v72, v127
	v_mov_b32_e32 v119, v127
	v_mov_b32_e32 v118, v127
	v_mov_b32_e32 v117, v127
	v_mov_b32_e32 v116, v127
	v_mov_b32_e32 v115, v127
	v_mov_b32_e32 v114, v127
	v_mov_b32_e32 v113, v127
	v_mov_b32_e32 v112, v127
	v_mov_b32_e32 v103, v127
	v_mov_b32_e32 v102, v127
	v_mov_b32_e32 v101, v127
	v_mov_b32_e32 v100, v127
	v_mov_b32_e32 v99, v127
	v_mov_b32_e32 v98, v127
	v_mov_b32_e32 v97, v127
	v_mov_b32_e32 v96, v127
	v_mov_b32_e32 v87, v127
	v_mov_b32_e32 v86, v127
	v_mov_b32_e32 v85, v127
	v_mov_b32_e32 v84, v127
	v_mov_b32_e32 v83, v127
	v_mov_b32_e32 v82, v127
	v_mov_b32_e32 v81, v127
	v_mov_b32_e32 v80, v127
	v_mov_b32_e32 v71, v127
	v_mov_b32_e32 v70, v127
	v_mov_b32_e32 v69, v127
	v_mov_b32_e32 v68, v127
	v_mov_b32_e32 v67, v127
	v_mov_b32_e32 v66, v127
	v_mov_b32_e32 v65, v127
	v_mov_b32_e32 v64, v127
	v_mov_b32_e32 v63, v127
	v_mov_b32_e32 v62, v127
	v_mov_b32_e32 v61, v127
	v_mov_b32_e32 v60, v127
	v_mov_b32_e32 v59, v127
	v_mov_b32_e32 v58, v127
	v_mov_b32_e32 v57, v127
	v_mov_b32_e32 v56, v127
	v_mov_b32_e32 v47, v127
	v_mov_b32_e32 v46, v127
	v_mov_b32_e32 v45, v127
	v_mov_b32_e32 v44, v127
	v_mov_b32_e32 v43, v127
	v_mov_b32_e32 v42, v127
	v_mov_b32_e32 v41, v127
	v_mov_b32_e32 v40, v127
	v_mov_b32_e32 v31, v127
	v_mov_b32_e32 v30, v127
	v_mov_b32_e32 v29, v127
	v_mov_b32_e32 v28, v127
	v_mov_b32_e32 v27, v127
	v_mov_b32_e32 v26, v127
	v_mov_b32_e32 v25, v127
	v_mov_b32_e32 v24, v127
	v_mov_b32_e32 v15, v127
	v_mov_b32_e32 v14, v127
	v_mov_b32_e32 v13, v127
	v_mov_b32_e32 v12, v127
	v_mov_b32_e32 v11, v127
	v_mov_b32_e32 v10, v127
	v_mov_b32_e32 v9, v127
	v_mov_b32_e32 v8, v127
	v_mov_b32_e32 v55, v127
	v_mov_b32_e32 v54, v127
	v_mov_b32_e32 v53, v127
	v_mov_b32_e32 v52, v127
	v_mov_b32_e32 v51, v127
	v_mov_b32_e32 v50, v127
	v_mov_b32_e32 v49, v127
	v_mov_b32_e32 v48, v127
	v_mov_b32_e32 v39, v127
	v_mov_b32_e32 v38, v127
	v_mov_b32_e32 v37, v127
	v_mov_b32_e32 v36, v127
	v_mov_b32_e32 v35, v127
	v_mov_b32_e32 v34, v127
	v_mov_b32_e32 v33, v127
	v_mov_b32_e32 v32, v127
	v_mov_b32_e32 v23, v127
	v_mov_b32_e32 v22, v127
	v_mov_b32_e32 v21, v127
	v_mov_b32_e32 v20, v127
	v_mov_b32_e32 v19, v127
	v_mov_b32_e32 v18, v127
	v_mov_b32_e32 v17, v127
	v_mov_b32_e32 v16, v127
	v_mov_b32_e32 v7, v127
	v_mov_b32_e32 v6, v127
	v_mov_b32_e32 v5, v127
	v_mov_b32_e32 v4, v127
	v_mov_b32_e32 v3, v127
	v_mov_b32_e32 v2, v127
	s_waitcnt lgkmcnt(0)
	v_mov_b32_e32 v1, v127
	v_mov_b32_e32 v0, v127
	s_cbranch_vccnz .LBB0_120
	s_add_u32 s39, s14, 0x100
	s_addc_u32 s40, s15, 0
	s_add_u32 s14, s16, 0x80
	v_mov_b32_e32 v0, 0
	s_addc_u32 s15, s17, 0
	s_mov_b32 s16, 0
	v_mov_b32_e32 v1, v0
	v_mov_b32_e32 v2, v0
	v_mov_b32_e32 v3, v0
	v_mov_b32_e32 v4, v0
	v_mov_b32_e32 v5, v0
	v_mov_b32_e32 v6, v0
	v_mov_b32_e32 v7, v0
	v_mov_b32_e32 v16, v0
	v_mov_b32_e32 v17, v0
	v_mov_b32_e32 v18, v0
	v_mov_b32_e32 v19, v0
	v_mov_b32_e32 v20, v0
	v_mov_b32_e32 v21, v0
	v_mov_b32_e32 v22, v0
	v_mov_b32_e32 v23, v0
	v_mov_b32_e32 v32, v0
	v_mov_b32_e32 v33, v0
	v_mov_b32_e32 v34, v0
	v_mov_b32_e32 v35, v0
	v_mov_b32_e32 v36, v0
	v_mov_b32_e32 v37, v0
	v_mov_b32_e32 v38, v0
	v_mov_b32_e32 v39, v0
	v_mov_b32_e32 v48, v0
	v_mov_b32_e32 v49, v0
	v_mov_b32_e32 v50, v0
	v_mov_b32_e32 v51, v0
	v_mov_b32_e32 v52, v0
	v_mov_b32_e32 v53, v0
	v_mov_b32_e32 v54, v0
	v_mov_b32_e32 v55, v0
	v_mov_b32_e32 v8, v0
	v_mov_b32_e32 v9, v0
	v_mov_b32_e32 v10, v0
	v_mov_b32_e32 v11, v0
	v_mov_b32_e32 v12, v0
	v_mov_b32_e32 v13, v0
	v_mov_b32_e32 v14, v0
	v_mov_b32_e32 v15, v0
	v_mov_b32_e32 v24, v0
	v_mov_b32_e32 v25, v0
	v_mov_b32_e32 v26, v0
	v_mov_b32_e32 v27, v0
	v_mov_b32_e32 v28, v0
	v_mov_b32_e32 v29, v0
	v_mov_b32_e32 v30, v0
	v_mov_b32_e32 v31, v0
	v_mov_b32_e32 v40, v0
	v_mov_b32_e32 v41, v0
	v_mov_b32_e32 v42, v0
	v_mov_b32_e32 v43, v0
	v_mov_b32_e32 v44, v0
	v_mov_b32_e32 v45, v0
	v_mov_b32_e32 v46, v0
	v_mov_b32_e32 v47, v0
	v_mov_b32_e32 v56, v0
	v_mov_b32_e32 v57, v0
	v_mov_b32_e32 v58, v0
	v_mov_b32_e32 v59, v0
	v_mov_b32_e32 v60, v0
	v_mov_b32_e32 v61, v0
	v_mov_b32_e32 v62, v0
	v_mov_b32_e32 v63, v0
	v_mov_b32_e32 v64, v0
	v_mov_b32_e32 v65, v0
	v_mov_b32_e32 v66, v0
	v_mov_b32_e32 v67, v0
	v_mov_b32_e32 v68, v0
	v_mov_b32_e32 v69, v0
	v_mov_b32_e32 v70, v0
	v_mov_b32_e32 v71, v0
	v_mov_b32_e32 v80, v0
	v_mov_b32_e32 v81, v0
	v_mov_b32_e32 v82, v0
	v_mov_b32_e32 v83, v0
	v_mov_b32_e32 v84, v0
	v_mov_b32_e32 v85, v0
	v_mov_b32_e32 v86, v0
	v_mov_b32_e32 v87, v0
	v_mov_b32_e32 v96, v0
	v_mov_b32_e32 v97, v0
	v_mov_b32_e32 v98, v0
	v_mov_b32_e32 v99, v0
	v_mov_b32_e32 v100, v0
	v_mov_b32_e32 v101, v0
	v_mov_b32_e32 v102, v0
	v_mov_b32_e32 v103, v0
	v_mov_b32_e32 v112, v0
	v_mov_b32_e32 v113, v0
	v_mov_b32_e32 v114, v0
	v_mov_b32_e32 v115, v0
	v_mov_b32_e32 v116, v0
	v_mov_b32_e32 v117, v0
	v_mov_b32_e32 v118, v0
	v_mov_b32_e32 v119, v0
	v_mov_b32_e32 v72, v0
	v_mov_b32_e32 v73, v0
	v_mov_b32_e32 v74, v0
	v_mov_b32_e32 v75, v0
	v_mov_b32_e32 v76, v0
	v_mov_b32_e32 v77, v0
	v_mov_b32_e32 v78, v0
	v_mov_b32_e32 v79, v0
	v_mov_b32_e32 v88, v0
	v_mov_b32_e32 v89, v0
	v_mov_b32_e32 v90, v0
	v_mov_b32_e32 v91, v0
	v_mov_b32_e32 v92, v0
	v_mov_b32_e32 v93, v0
	v_mov_b32_e32 v94, v0
	v_mov_b32_e32 v95, v0
	v_mov_b32_e32 v104, v0
	v_mov_b32_e32 v105, v0
	v_mov_b32_e32 v106, v0
	v_mov_b32_e32 v107, v0
	v_mov_b32_e32 v108, v0
	v_mov_b32_e32 v109, v0
	v_mov_b32_e32 v110, v0
	v_mov_b32_e32 v111, v0
	v_mov_b32_e32 v120, v0
	v_mov_b32_e32 v121, v0
	v_mov_b32_e32 v122, v0
	v_mov_b32_e32 v123, v0
	v_mov_b32_e32 v124, v0
	v_mov_b32_e32 v125, v0
	v_mov_b32_e32 v126, v0
	v_mov_b32_e32 v127, v0
	s_mov_b64 s[44:45], 0x80
	v_readfirstlane_b32 s90, v192
	s_lshr_b32 s90, s90, 8
	s_cmp_eq_u32 s90, 1
	s_cbranch_scc0 .Lprio_skip_0
	s_setprio 1
; #define PG8_STAGE(bufoff, gbase, voff) do { _Pragma("unroll") for (int _i = 0; _i < 2; ++_i) \
;         __builtin_amdgcn_global_load_lds((const unsigned*)((const char*)(gbase) + (voff)[_i]), (LAS unsigned*)(lds + (bufoff) + ldsw + _i * 8192), 16, 0, 0); } while (0)
; #define PG8_LDA(dst, b, h) do { _Pragma("unroll") for (int m = 0; m < 4; ++m) _Pragma("unroll") for (int k = 0; k < 2; ++k) dst[m][k] = *(const LAS bf16x8*)(lds + PG8_SA(b, h) + aoff + m * 2048 + k * 1024); } while (0)
; #define PG8_LDB(dst, b, h) do { _Pragma("unroll") for (int n = 0; n < 2; ++n) _Pragma("unroll") for (int k = 0; k < 2; ++k) dst[n][k] = *(const LAS bf16x8*)(lds + PG8_SB(b, h) + boff + n * 2048 + k * 1024); } while (0)
; #define PG8_MMA(ai, bj, At, Bt) do { __builtin_amdgcn_s_setprio(1); _Pragma("unroll") for (int m = 0; m < 4; ++m) _Pragma("unroll") for (int n = 0; n < 2; ++n) _Pragma("unroll") for (int k = 0; k < 2; ++k) \
;         acc[ai][bj][m][n] = __builtin_amdgcn_mfma_f32_16x16x32_bf16(Bt[n][k], At[m][k], acc[ai][bj][m][n], 0, 0, 0); __builtin_amdgcn_s_setprio(0); } while (0)
; #define PG8_WAIT_L(n) asm volatile("s_waitcnt lgkmcnt(" #n ")" ::: "memory")
; #define PG8_BAR __builtin_amdgcn_s_barrier()
; #define PG8_SCHED __builtin_amdgcn_sched_barrier(0)
; template <class Epi>
; __device__ __forceinline__ void gemm_phase(LAS unsigned char* lds, const Gemm g, const StaticOrder& S, const Epi& E) {
;     ...
;         for (int t = 0; t < nt; t += 2) {
;             const bool last = (t == nt - 2);
;             const char* a1 = cA + (size_t)(t + 1) * kstep;
;             const char* a2 = last ? nA : cA + (size_t)(t + 2) * kstep; const char* b2 = last ? nB : cB + (size_t)(t + 2) * kstep;
;             const char* a3 = a2 + kstep; const char* b3 = b2 + kstep;
;             PG8_LDB(B0, 0, 0); PG8_SCHED; PG8_LDA(At, 0, 0); PG8_STAGE(PG8_SA(1, 1), a1 + hstep, voffA);
;             PG8_WAIT_L(8); PG8_BAR; PG8_WAIT_L(0); PG8_MMA(0, 0, At, B0); PG8_BAR; PG8_SCHED;
;             PG8_LDB(B1, 0, 1); PG8_STAGE(PG8_SB(0, 0), b2, voffB);
;             PG8_BAR; PG8_WAIT_L(0); PG8_MMA(0, 1, At, B1); PG8_BAR;
;             PG8_LDA(At, 0, 1); PG8_STAGE(PG8_SA(0, 0), a2, voffA);
;             PG8_BAR; PG8_WAIT_L(0); PG8_MMA(1, 0, At, B0); PG8_BAR; PG8_SCHED;
.Lprio_skip_0:
.LBB0_119:
	s_add_i32 s41, s16, 2
	s_add_u32 s18, s14, 0x80
	s_addc_u32 s17, s15, 0
	s_add_i32 s42, 0, 0x10000
	v_add_u32_e32 v140, s42, v245
	ds_read_b128 v[128:131], v140
	ds_read_b128 v[132:135], v140 offset:1024
	ds_read_b128 v[136:139], v140 offset:2048
	ds_read_b128 v[140:143], v140 offset:3072
	s_cmp_eq_u32 s31, s16
	s_cselect_b32 s16, s10, s18
	s_cselect_b32 s17, s11, s17
	s_cselect_b32 s19, s13, s40
	s_cselect_b32 s18, s12, s39
	v_lshl_add_u64 v[176:177], s[14:15], 0, v[210:211]
	s_add_i32 m0, s24, 0xc000
	ds_read_b128 v[144:147], v247
	ds_read_b128 v[148:151], v247 offset:1024
	ds_read_b128 v[152:155], v247 offset:2048
	ds_read_b128 v[156:159], v247 offset:3072
	ds_read_b128 v[160:163], v247 offset:4096
	ds_read_b128 v[164:167], v247 offset:5120
	ds_read_b128 v[168:171], v247 offset:6144
	ds_read_b128 v[172:175], v247 offset:7168
	global_load_lds_dwordx4 v[176:177], off
	v_lshl_add_u64 v[176:177], s[14:15], 0, v[208:209]
	s_add_i32 m0, s24, 0xe000
	s_nop 0
	global_load_lds_dwordx4 v[176:177], off
	s_waitcnt lgkmcnt(8)
	s_barrier
	s_waitcnt lgkmcnt(0)
	s_waitcnt lgkmcnt(0)
	v_mfma_f32_16x16x32_bf16 v[124:127], v[128:131], v[144:147], v[124:127]
	v_mfma_f32_16x16x32_bf16 v[120:123], v[136:139], v[144:147], v[120:123]
	v_mfma_f32_16x16x32_bf16 v[108:111], v[128:131], v[152:155], v[108:111]
	v_mfma_f32_16x16x32_bf16 v[104:107], v[136:139], v[152:155], v[104:107]
	v_mfma_f32_16x16x32_bf16 v[92:95], v[128:131], v[160:163], v[92:95]
	v_mfma_f32_16x16x32_bf16 v[88:91], v[136:139], v[160:163], v[88:91]
	v_mfma_f32_16x16x32_bf16 v[76:79], v[128:131], v[168:171], v[76:79]
	v_mfma_f32_16x16x32_bf16 v[72:75], v[136:139], v[168:171], v[72:75]
	v_mfma_f32_16x16x32_bf16 v[124:127], v[132:135], v[148:151], v[124:127]
	v_mfma_f32_16x16x32_bf16 v[120:123], v[140:143], v[148:151], v[120:123]
	v_mfma_f32_16x16x32_bf16 v[108:111], v[132:135], v[156:159], v[108:111]
	v_mfma_f32_16x16x32_bf16 v[104:107], v[140:143], v[156:159], v[104:107]
	v_mfma_f32_16x16x32_bf16 v[92:95], v[132:135], v[164:167], v[92:95]
	v_mfma_f32_16x16x32_bf16 v[88:91], v[140:143], v[164:167], v[88:91]
	v_mfma_f32_16x16x32_bf16 v[76:79], v[132:135], v[172:175], v[76:79]
	v_mfma_f32_16x16x32_bf16 v[72:75], v[140:143], v[172:175], v[72:75]
	s_barrier
	s_add_i32 s43, 0, 0x14000
	s_add_i32 s42, s42, s23
	v_add_u32_e32 v188, s43, v245
	v_lshl_add_u64 v[212:213], s[18:19], 0, v[194:195]
	s_mov_b32 m0, s42
	ds_read_b128 v[176:179], v188
	ds_read_b128 v[180:183], v188 offset:1024
	ds_read_b128 v[184:187], v188 offset:2048
	ds_read_b128 v[188:191], v188 offset:3072
	global_load_lds_dwordx4 v[212:213], off
	v_lshl_add_u64 v[214:215], s[18:19], 0, v[206:207]
	s_add_i32 m0, s42, 0x2000
	s_nop 0
	global_load_lds_dwordx4 v[214:215], off
	s_barrier
	s_waitcnt lgkmcnt(0)
	s_waitcnt lgkmcnt(0)
	v_mfma_f32_16x16x32_bf16 v[116:119], v[176:179], v[144:147], v[116:119]
	v_mfma_f32_16x16x32_bf16 v[112:115], v[184:187], v[144:147], v[112:115]
	v_mfma_f32_16x16x32_bf16 v[100:103], v[176:179], v[152:155], v[100:103]
	v_mfma_f32_16x16x32_bf16 v[96:99], v[184:187], v[152:155], v[96:99]
	v_mfma_f32_16x16x32_bf16 v[84:87], v[176:179], v[160:163], v[84:87]
	v_mfma_f32_16x16x32_bf16 v[80:83], v[184:187], v[160:163], v[80:83]
	v_mfma_f32_16x16x32_bf16 v[68:71], v[176:179], v[168:171], v[68:71]
	v_mfma_f32_16x16x32_bf16 v[64:67], v[184:187], v[168:171], v[64:67]
	v_mfma_f32_16x16x32_bf16 v[116:119], v[180:183], v[148:151], v[116:119]
	v_mfma_f32_16x16x32_bf16 v[112:115], v[188:191], v[148:151], v[112:115]
	v_mfma_f32_16x16x32_bf16 v[100:103], v[180:183], v[156:159], v[100:103]
	v_mfma_f32_16x16x32_bf16 v[96:99], v[188:191], v[156:159], v[96:99]
	v_mfma_f32_16x16x32_bf16 v[84:87], v[180:183], v[164:167], v[84:87]
	v_mfma_f32_16x16x32_bf16 v[80:83], v[188:191], v[164:167], v[80:83]
	v_mfma_f32_16x16x32_bf16 v[68:71], v[180:183], v[172:175], v[68:71]
	v_mfma_f32_16x16x32_bf16 v[64:67], v[188:191], v[172:175], v[64:67]
	s_mov_b32 m0, s24
	v_lshl_add_u64 v[216:217], s[16:17], 0, v[202:203]
	s_barrier
	ds_read_b128 v[144:147], v247 offset:16384
	ds_read_b128 v[148:151], v247 offset:17408
	ds_read_b128 v[152:155], v247 offset:18432
	ds_read_b128 v[156:159], v247 offset:19456
	ds_read_b128 v[160:163], v247 offset:20480
	ds_read_b128 v[164:167], v247 offset:21504
	ds_read_b128 v[168:171], v247 offset:22528
	ds_read_b128 v[172:175], v247 offset:23552
	global_load_lds_dwordx4 v[216:217], off
	v_lshl_add_u64 v[218:219], s[16:17], 0, v[204:205]
	s_mov_b32 m0, s25
	s_nop 0
	global_load_lds_dwordx4 v[218:219], off
	s_barrier
	s_waitcnt lgkmcnt(0)
	s_waitcnt lgkmcnt(0)
	v_mfma_f32_16x16x32_bf16 v[60:63], v[128:131], v[144:147], v[60:63]
	v_mfma_f32_16x16x32_bf16 v[56:59], v[136:139], v[144:147], v[56:59]
	v_mfma_f32_16x16x32_bf16 v[44:47], v[128:131], v[152:155], v[44:47]
	v_mfma_f32_16x16x32_bf16 v[40:43], v[136:139], v[152:155], v[40:43]
	v_mfma_f32_16x16x32_bf16 v[28:31], v[128:131], v[160:163], v[28:31]
	v_mfma_f32_16x16x32_bf16 v[24:27], v[136:139], v[160:163], v[24:27]
	v_mfma_f32_16x16x32_bf16 v[12:15], v[128:131], v[168:171], v[12:15]
	v_mfma_f32_16x16x32_bf16 v[8:11], v[136:139], v[168:171], v[8:11]
	v_mfma_f32_16x16x32_bf16 v[60:63], v[132:135], v[148:151], v[60:63]
	v_mfma_f32_16x16x32_bf16 v[56:59], v[140:143], v[148:151], v[56:59]
	v_mfma_f32_16x16x32_bf16 v[44:47], v[132:135], v[156:159], v[44:47]
	v_mfma_f32_16x16x32_bf16 v[40:43], v[140:143], v[156:159], v[40:43]
	v_mfma_f32_16x16x32_bf16 v[28:31], v[132:135], v[164:167], v[28:31]
	v_mfma_f32_16x16x32_bf16 v[24:27], v[140:143], v[164:167], v[24:27]
	v_mfma_f32_16x16x32_bf16 v[12:15], v[132:135], v[172:175], v[12:15]
	v_mfma_f32_16x16x32_bf16 v[8:11], v[140:143], v[172:175], v[8:11]
	s_barrier
; #define PG8_STAGE(bufoff, gbase, voff) do { _Pragma("unroll") for (int _i = 0; _i < 2; ++_i) \
;         __builtin_amdgcn_global_load_lds((const unsigned*)((const char*)(gbase) + (voff)[_i]), (LAS unsigned*)(lds + (bufoff) + ldsw + _i * 8192), 16, 0, 0); } while (0)
; #define PG8_LDA(dst, b, h) do { _Pragma("unroll") for (int m = 0; m < 4; ++m) _Pragma("unroll") for (int k = 0; k < 2; ++k) dst[m][k] = *(const LAS bf16x8*)(lds + PG8_SA(b, h) + aoff + m * 2048 + k * 1024); } while (0)
; #define PG8_LDB(dst, b, h) do { _Pragma("unroll") for (int n = 0; n < 2; ++n) _Pragma("unroll") for (int k = 0; k < 2; ++k) dst[n][k] = *(const LAS bf16x8*)(lds + PG8_SB(b, h) + boff + n * 2048 + k * 1024); } while (0)
; #define PG8_MMA(ai, bj, At, Bt) do { __builtin_amdgcn_s_setprio(1); _Pragma("unroll") for (int m = 0; m < 4; ++m) _Pragma("unroll") for (int n = 0; n < 2; ++n) _Pragma("unroll") for (int k = 0; k < 2; ++k) \
;         acc[ai][bj][m][n] = __builtin_amdgcn_mfma_f32_16x16x32_bf16(Bt[n][k], At[m][k], acc[ai][bj][m][n], 0, 0, 0); __builtin_amdgcn_s_setprio(0); } while (0)
; #define PG8_WAIT_V(n) asm volatile("s_waitcnt vmcnt(" #n ")" ::: "memory")
; #define PG8_WAIT_L(n) asm volatile("s_waitcnt lgkmcnt(" #n ")" ::: "memory")
; #define PG8_BAR __builtin_amdgcn_s_barrier()
; #define PG8_SCHED __builtin_amdgcn_sched_barrier(0)
; template <class Epi>
; __device__ __forceinline__ void gemm_phase(LAS unsigned char* lds, const Gemm g, const StaticOrder& S, const Epi& E) {
;     ...
;             PG8_STAGE(PG8_SB(0, 1), b2 + hstep, voffB);
;             PG8_WAIT_V(6); PG8_BAR; PG8_MMA(1, 1, At, B1); PG8_BAR;
;             PG8_LDB(B0, 1, 0); PG8_SCHED; PG8_LDA(At, 1, 0); PG8_STAGE(PG8_SA(0, 1), a2 + hstep, voffA);
;             PG8_WAIT_L(8); PG8_BAR; PG8_WAIT_L(0); PG8_MMA(0, 0, At, B0); PG8_BAR; PG8_SCHED;
;             PG8_LDB(B1, 1, 1); PG8_STAGE(PG8_SB(1, 0), b3, voffB);
;             PG8_BAR; PG8_WAIT_L(0); PG8_MMA(0, 1, At, B1); PG8_BAR;
;             PG8_LDA(At, 1, 1); PG8_STAGE(PG8_SA(1, 0), a3, voffA);
	s_add_u32 s18, s18, s0
	s_addc_u32 s19, s19, s1
	s_add_i32 s42, s43, s23
	v_lshl_add_u64 v[220:221], s[18:19], 0, v[194:195]
	s_mov_b32 m0, s42
	v_lshl_add_u64 v[222:223], s[18:19], 0, v[206:207]
	global_load_lds_dwordx4 v[220:221], off
	s_add_i32 m0, s42, 0x2000
	s_nop 0
	global_load_lds_dwordx4 v[222:223], off
	s_waitcnt vmcnt(6)
	s_barrier
	v_mfma_f32_16x16x32_bf16 v[52:55], v[176:179], v[144:147], v[52:55]
	v_mfma_f32_16x16x32_bf16 v[48:51], v[184:187], v[144:147], v[48:51]
	v_mfma_f32_16x16x32_bf16 v[36:39], v[176:179], v[152:155], v[36:39]
	v_mfma_f32_16x16x32_bf16 v[32:35], v[184:187], v[152:155], v[32:35]
	v_mfma_f32_16x16x32_bf16 v[20:23], v[176:179], v[160:163], v[20:23]
	v_mfma_f32_16x16x32_bf16 v[16:19], v[184:187], v[160:163], v[16:19]
	v_mfma_f32_16x16x32_bf16 v[4:7], v[176:179], v[168:171], v[4:7]
	v_mfma_f32_16x16x32_bf16 v[0:3], v[184:187], v[168:171], v[0:3]
	v_mfma_f32_16x16x32_bf16 v[52:55], v[180:183], v[148:151], v[52:55]
	v_mfma_f32_16x16x32_bf16 v[48:51], v[188:191], v[148:151], v[48:51]
	v_mfma_f32_16x16x32_bf16 v[36:39], v[180:183], v[156:159], v[36:39]
	v_mfma_f32_16x16x32_bf16 v[32:35], v[188:191], v[156:159], v[32:35]
	v_mfma_f32_16x16x32_bf16 v[20:23], v[180:183], v[164:167], v[20:23]
	v_mfma_f32_16x16x32_bf16 v[16:19], v[188:191], v[164:167], v[16:19]
	v_mfma_f32_16x16x32_bf16 v[4:7], v[180:183], v[172:175], v[4:7]
	v_mfma_f32_16x16x32_bf16 v[0:3], v[188:191], v[172:175], v[0:3]
	s_add_i32 s18, 0, 0x18000
	v_add_u32_e32 v140, s18, v245
	s_barrier
	ds_read_b128 v[128:131], v140
	ds_read_b128 v[132:135], v140 offset:1024
	ds_read_b128 v[136:139], v140 offset:2048
	ds_read_b128 v[140:143], v140 offset:3072
	s_add_u32 s16, s16, s0
	s_addc_u32 s17, s17, s1
	s_mov_b32 m0, s26
	v_lshl_add_u64 v[176:177], s[16:17], 0, v[202:203]
	ds_read_b128 v[144:147], v247 offset:32768
	ds_read_b128 v[148:151], v247 offset:33792
	ds_read_b128 v[152:155], v247 offset:34816
	ds_read_b128 v[156:159], v247 offset:35840
	ds_read_b128 v[160:163], v247 offset:36864
	ds_read_b128 v[164:167], v247 offset:37888
	ds_read_b128 v[168:171], v247 offset:38912
	ds_read_b128 v[172:175], v247 offset:39936
	global_load_lds_dwordx4 v[176:177], off
	v_lshl_add_u64 v[176:177], s[16:17], 0, v[204:205]
	s_mov_b32 m0, s27
	s_nop 0
	global_load_lds_dwordx4 v[176:177], off
	s_waitcnt lgkmcnt(8)
	s_barrier
	s_waitcnt lgkmcnt(0)
	s_waitcnt lgkmcnt(0)
	v_mfma_f32_16x16x32_bf16 v[124:127], v[128:131], v[144:147], v[124:127]
	v_mfma_f32_16x16x32_bf16 v[120:123], v[136:139], v[144:147], v[120:123]
	v_mfma_f32_16x16x32_bf16 v[108:111], v[128:131], v[152:155], v[108:111]
	v_mfma_f32_16x16x32_bf16 v[104:107], v[136:139], v[152:155], v[104:107]
	v_mfma_f32_16x16x32_bf16 v[92:95], v[128:131], v[160:163], v[92:95]
	v_mfma_f32_16x16x32_bf16 v[88:91], v[136:139], v[160:163], v[88:91]
	v_mfma_f32_16x16x32_bf16 v[76:79], v[128:131], v[168:171], v[76:79]
	v_mfma_f32_16x16x32_bf16 v[72:75], v[136:139], v[168:171], v[72:75]
	v_mfma_f32_16x16x32_bf16 v[124:127], v[132:135], v[148:151], v[124:127]
	v_mfma_f32_16x16x32_bf16 v[120:123], v[140:143], v[148:151], v[120:123]
	v_mfma_f32_16x16x32_bf16 v[108:111], v[132:135], v[156:159], v[108:111]
	v_mfma_f32_16x16x32_bf16 v[104:107], v[140:143], v[156:159], v[104:107]
	v_mfma_f32_16x16x32_bf16 v[92:95], v[132:135], v[164:167], v[92:95]
	v_mfma_f32_16x16x32_bf16 v[88:91], v[140:143], v[164:167], v[88:91]
	v_mfma_f32_16x16x32_bf16 v[76:79], v[132:135], v[172:175], v[76:79]
	v_mfma_f32_16x16x32_bf16 v[72:75], v[140:143], v[172:175], v[72:75]
	s_barrier
	s_add_i32 s16, 0, 0x1c000
	s_add_i32 s17, s18, s23
	v_add_u32_e32 v188, s16, v245
	v_lshl_add_u64 v[212:213], v[212:213], 0, s[44:45]
	s_mov_b32 m0, s17
	ds_read_b128 v[176:179], v188
	ds_read_b128 v[180:183], v188 offset:1024
	ds_read_b128 v[184:187], v188 offset:2048
	ds_read_b128 v[188:191], v188 offset:3072
	global_load_lds_dwordx4 v[212:213], off
	v_lshl_add_u64 v[212:213], v[214:215], 0, s[44:45]
	s_add_i32 m0, s17, 0x2000
	s_nop 0
	global_load_lds_dwordx4 v[212:213], off
	s_barrier
	s_waitcnt lgkmcnt(0)
	s_waitcnt lgkmcnt(0)
	v_mfma_f32_16x16x32_bf16 v[116:119], v[176:179], v[144:147], v[116:119]
	v_mfma_f32_16x16x32_bf16 v[112:115], v[184:187], v[144:147], v[112:115]
	v_mfma_f32_16x16x32_bf16 v[100:103], v[176:179], v[152:155], v[100:103]
	v_mfma_f32_16x16x32_bf16 v[96:99], v[184:187], v[152:155], v[96:99]
	v_mfma_f32_16x16x32_bf16 v[84:87], v[176:179], v[160:163], v[84:87]
	v_mfma_f32_16x16x32_bf16 v[80:83], v[184:187], v[160:163], v[80:83]
	v_mfma_f32_16x16x32_bf16 v[68:71], v[176:179], v[168:171], v[68:71]
	v_mfma_f32_16x16x32_bf16 v[64:67], v[184:187], v[168:171], v[64:67]
	v_mfma_f32_16x16x32_bf16 v[116:119], v[180:183], v[148:151], v[116:119]
	v_mfma_f32_16x16x32_bf16 v[112:115], v[188:191], v[148:151], v[112:115]
	v_mfma_f32_16x16x32_bf16 v[100:103], v[180:183], v[156:159], v[100:103]
	v_mfma_f32_16x16x32_bf16 v[96:99], v[188:191], v[156:159], v[96:99]
	v_mfma_f32_16x16x32_bf16 v[84:87], v[180:183], v[164:167], v[84:87]
	v_mfma_f32_16x16x32_bf16 v[80:83], v[188:191], v[164:167], v[80:83]
	v_mfma_f32_16x16x32_bf16 v[68:71], v[180:183], v[172:175], v[68:71]
	v_mfma_f32_16x16x32_bf16 v[64:67], v[188:191], v[172:175], v[64:67]
	s_mov_b32 m0, s28
	v_lshl_add_u64 v[212:213], v[216:217], 0, s[44:45]
	s_barrier
	ds_read_b128 v[144:147], v247 offset:49152
	ds_read_b128 v[148:151], v247 offset:50176
	ds_read_b128 v[152:155], v247 offset:51200
	ds_read_b128 v[156:159], v247 offset:52224
	ds_read_b128 v[160:163], v247 offset:53248
	ds_read_b128 v[164:167], v247 offset:54272
	ds_read_b128 v[168:171], v247 offset:55296
	ds_read_b128 v[172:175], v247 offset:56320
	global_load_lds_dwordx4 v[212:213], off
	v_lshl_add_u64 v[212:213], v[218:219], 0, s[44:45]
	s_mov_b32 m0, s29
	s_nop 0
	global_load_lds_dwordx4 v[212:213], off
	s_barrier
; #define PG8_STAGE(bufoff, gbase, voff) do { _Pragma("unroll") for (int _i = 0; _i < 2; ++_i) \
;         __builtin_amdgcn_global_load_lds((const unsigned*)((const char*)(gbase) + (voff)[_i]), (LAS unsigned*)(lds + (bufoff) + ldsw + _i * 8192), 16, 0, 0); } while (0)
; #define PG8_MMA(ai, bj, At, Bt) do { __builtin_amdgcn_s_setprio(1); _Pragma("unroll") for (int m = 0; m < 4; ++m) _Pragma("unroll") for (int n = 0; n < 2; ++n) _Pragma("unroll") for (int k = 0; k < 2; ++k) \
;         acc[ai][bj][m][n] = __builtin_amdgcn_mfma_f32_16x16x32_bf16(Bt[n][k], At[m][k], acc[ai][bj][m][n], 0, 0, 0); __builtin_amdgcn_s_setprio(0); } while (0)
; #define PG8_WAIT_V(n) asm volatile("s_waitcnt vmcnt(" #n ")" ::: "memory")
; #define PG8_WAIT_L(n) asm volatile("s_waitcnt lgkmcnt(" #n ")" ::: "memory")
; #define PG8_BAR __builtin_amdgcn_s_barrier()
; #define PG8_SCHED __builtin_amdgcn_sched_barrier(0)
; template <class Epi>
; __device__ __forceinline__ void gemm_phase(LAS unsigned char* lds, const Gemm g, const StaticOrder& S, const Epi& E) {
;     ...
;             PG8_BAR; PG8_WAIT_L(0); PG8_MMA(1, 0, At, B0); PG8_BAR; PG8_SCHED;
;             PG8_STAGE(PG8_SB(1, 1), b3 + hstep, voffB);
;             PG8_WAIT_V(6); PG8_BAR; PG8_MMA(1, 1, At, B1); PG8_BAR;
;         }
	s_waitcnt lgkmcnt(0)
	s_waitcnt lgkmcnt(0)
	v_mfma_f32_16x16x32_bf16 v[60:63], v[128:131], v[144:147], v[60:63]
	v_mfma_f32_16x16x32_bf16 v[56:59], v[136:139], v[144:147], v[56:59]
	v_mfma_f32_16x16x32_bf16 v[44:47], v[128:131], v[152:155], v[44:47]
	v_mfma_f32_16x16x32_bf16 v[40:43], v[136:139], v[152:155], v[40:43]
	v_mfma_f32_16x16x32_bf16 v[28:31], v[128:131], v[160:163], v[28:31]
	v_mfma_f32_16x16x32_bf16 v[24:27], v[136:139], v[160:163], v[24:27]
	v_mfma_f32_16x16x32_bf16 v[12:15], v[128:131], v[168:171], v[12:15]
	v_mfma_f32_16x16x32_bf16 v[8:11], v[136:139], v[168:171], v[8:11]
	v_mfma_f32_16x16x32_bf16 v[60:63], v[132:135], v[148:151], v[60:63]
	v_mfma_f32_16x16x32_bf16 v[56:59], v[140:143], v[148:151], v[56:59]
	v_mfma_f32_16x16x32_bf16 v[44:47], v[132:135], v[156:159], v[44:47]
	v_mfma_f32_16x16x32_bf16 v[40:43], v[140:143], v[156:159], v[40:43]
	v_mfma_f32_16x16x32_bf16 v[28:31], v[132:135], v[164:167], v[28:31]
	v_mfma_f32_16x16x32_bf16 v[24:27], v[140:143], v[164:167], v[24:27]
	v_mfma_f32_16x16x32_bf16 v[12:15], v[132:135], v[172:175], v[12:15]
	v_mfma_f32_16x16x32_bf16 v[8:11], v[140:143], v[172:175], v[8:11]
	s_barrier
	s_add_i32 s16, s16, s23
	v_lshl_add_u64 v[128:129], v[220:221], 0, s[44:45]
	s_mov_b32 m0, s16
	s_nop 0
	global_load_lds_dwordx4 v[128:129], off
	v_lshl_add_u64 v[128:129], v[222:223], 0, s[44:45]
	s_add_i32 m0, s16, 0x2000
	s_nop 0
	global_load_lds_dwordx4 v[128:129], off
	s_waitcnt vmcnt(6)
	s_barrier
	v_mfma_f32_16x16x32_bf16 v[52:55], v[176:179], v[144:147], v[52:55]
	v_mfma_f32_16x16x32_bf16 v[48:51], v[184:187], v[144:147], v[48:51]
	v_mfma_f32_16x16x32_bf16 v[36:39], v[176:179], v[152:155], v[36:39]
	v_mfma_f32_16x16x32_bf16 v[32:35], v[184:187], v[152:155], v[32:35]
	v_mfma_f32_16x16x32_bf16 v[20:23], v[176:179], v[160:163], v[20:23]
	v_mfma_f32_16x16x32_bf16 v[16:19], v[184:187], v[160:163], v[16:19]
	v_mfma_f32_16x16x32_bf16 v[4:7], v[176:179], v[168:171], v[4:7]
	v_mfma_f32_16x16x32_bf16 v[0:3], v[184:187], v[168:171], v[0:3]
	v_mfma_f32_16x16x32_bf16 v[52:55], v[180:183], v[148:151], v[52:55]
	v_mfma_f32_16x16x32_bf16 v[48:51], v[188:191], v[148:151], v[48:51]
	v_mfma_f32_16x16x32_bf16 v[36:39], v[180:183], v[156:159], v[36:39]
	v_mfma_f32_16x16x32_bf16 v[32:35], v[188:191], v[156:159], v[32:35]
	v_mfma_f32_16x16x32_bf16 v[20:23], v[180:183], v[164:167], v[20:23]
	v_mfma_f32_16x16x32_bf16 v[16:19], v[188:191], v[164:167], v[16:19]
	v_mfma_f32_16x16x32_bf16 v[4:7], v[180:183], v[172:175], v[4:7]
	v_mfma_f32_16x16x32_bf16 v[0:3], v[188:191], v[172:175], v[0:3]
	s_add_u32 s39, s39, 0x100
	s_addc_u32 s40, s40, 0
	s_add_u32 s14, s14, 0x100
	s_addc_u32 s15, s15, 0
	s_cmp_ge_i32 s41, s30
	s_mov_b32 s16, s41
	s_barrier
	s_cbranch_scc0 .LBB0_119
; #define LAS __attribute__((address_space(3)))
; __device__ __forceinline__ void unpack8(u32x4 w, float* f) { f[0] = bflo(w.x); f[1] = bfhi(w.x); f[2] = bflo(w.y); f[3] = bfhi(w.y); f[4] = bflo(w.z); f[5] = bfhi(w.z); f[6] = bflo(w.w); f[7] = bfhi(w.w); }
; __device__ __forceinline__ u32x4 pack8(const float* f) { u32x4 w; w.x = cvt_pk_bf16(f[0], f[1]); w.y = cvt_pk_bf16(f[2], f[3]); w.z = cvt_pk_bf16(f[4], f[5]); w.w = cvt_pk_bf16(f[6], f[7]); return w; }
;     __device__ __forceinline__ void operator()(const f32x4 (&acc)[2][2][4][2], const Unit& u, int wr, int wc, int fr, int fq, LAS unsigned char* lds, int par, int npm, int tid) const {
;         const int row0 = u.pm * BM + wr * 64 + fr, col0 = u.pn * BM + wc * 32 + 8 * fq;
;         u32x4 old[2][4][2];
; #pragma unroll
;         for (int ai = 0; ai < 2; ++ai)
; #pragma unroll
;             for (int m = 0; m < 4; ++m)
; #pragma unroll
;                 for (int bj = 0; bj < 2; ++bj) old[ai][m][bj] = *(const u32x4*)(Hb + (size_t)(row0 + ai * HALF + m * 16) * ldc + col0 + bj * HALF);
; #pragma unroll
;         for (int ai = 0; ai < 2; ++ai)
; #pragma unroll
;             for (int m = 0; m < 4; ++m) { const int row = row0 + ai * HALF + m * 16; bf16_t* hp = Hb + (size_t)row * ldc + col0;
;                 float part = 0.f;
; #pragma unroll
;                 for (int bj = 0; bj < 2; ++bj) { float o[8]; unpack8(old[ai][m][bj], o);
;                     const f32x4 a0 = acc[ai][bj][m][0], a1 = acc[ai][bj][m][1];
;                     float v[8] = {o[0] + a0[0], o[1] + a0[1], o[2] + a0[2], o[3] + a0[3], o[4] + a1[0], o[5] + a1[1], o[6] + a1[2], o[7] + a1[3]};
; #pragma unroll
;                     for (int k = 0; k < 8; ++k) part += v[k] * v[k];
;                     *(u32x4*)(hp + bj * HALF) = pack8(v); }
;                 part += __shfl_xor(part, 16); part += __shfl_xor(part, 32);
;                 if (fq == 0) atomicAdd(ssq + row, (unsigned long long)(part * 1048576.f)); }
.LBB0_120:
	s_setprio 0
	v_lshl_or_b32 v212, s38, 8, v246
	v_lshl_add_u32 v228, s37, 8, v201
	v_ashrrev_i32_e32 v213, 31, v212
	v_readlane_b32 s14, v254, 8
	v_lshlrev_b64 v[230:231], 1, v[212:213]
	v_readlane_b32 s15, v254, 9
	v_ashrrev_i32_e32 v229, 31, v228
	v_lshlrev_b64 v[232:233], 12, v[228:229]
	v_lshl_add_u64 v[132:133], s[14:15], 0, v[230:231]
	v_lshl_add_u64 v[128:129], v[132:133], 0, v[232:233]
	flat_load_dwordx4 v[188:191], v[128:129]
	flat_load_dwordx4 v[184:187], v[128:129] offset:256
	v_or_b32_e32 v226, 16, v228
	v_ashrrev_i32_e32 v227, 31, v226
	v_lshlrev_b64 v[128:129], 12, v[226:227]
	v_or_b32_e32 v224, 32, v228
	v_lshl_add_u64 v[128:129], v[132:133], 0, v[128:129]
	v_ashrrev_i32_e32 v225, 31, v224
	flat_load_dwordx4 v[180:183], v[128:129]
	flat_load_dwordx4 v[176:179], v[128:129] offset:256
	v_lshlrev_b64 v[128:129], 12, v[224:225]
	v_or_b32_e32 v222, 48, v228
	v_lshl_add_u64 v[128:129], v[132:133], 0, v[128:129]
	v_ashrrev_i32_e32 v223, 31, v222
	flat_load_dwordx4 v[172:175], v[128:129]
	flat_load_dwordx4 v[168:171], v[128:129] offset:256
	v_lshlrev_b64 v[128:129], 12, v[222:223]
	v_add_u32_e32 v220, 0x80, v228
	v_lshl_add_u64 v[128:129], v[132:133], 0, v[128:129]
	v_ashrrev_i32_e32 v221, 31, v220
	flat_load_dwordx4 v[164:167], v[128:129]
	flat_load_dwordx4 v[160:163], v[128:129] offset:256
	v_lshlrev_b64 v[128:129], 12, v[220:221]
	v_add_u32_e32 v218, 0x90, v228
	v_lshl_add_u64 v[128:129], v[132:133], 0, v[128:129]
	v_ashrrev_i32_e32 v219, 31, v218
	flat_load_dwordx4 v[156:159], v[128:129]
	flat_load_dwordx4 v[152:155], v[128:129] offset:256
	v_lshlrev_b64 v[128:129], 12, v[218:219]
	v_add_u32_e32 v216, 0xa0, v228
	v_add_u32_e32 v214, 0xb0, v228
	v_lshl_add_u64 v[128:129], v[132:133], 0, v[128:129]
	v_ashrrev_i32_e32 v217, 31, v216
	v_ashrrev_i32_e32 v215, 31, v214
	flat_load_dwordx4 v[148:151], v[128:129]
	flat_load_dwordx4 v[144:147], v[128:129] offset:256
	v_lshlrev_b64 v[128:129], 12, v[216:217]
	v_lshlrev_b64 v[134:135], 12, v[214:215]
	v_lshl_add_u64 v[128:129], v[132:133], 0, v[128:129]
	v_lshl_add_u64 v[132:133], v[132:133], 0, v[134:135]
	flat_load_dwordx4 v[136:139], v[128:129]
	s_nop 0
	flat_load_dwordx4 v[128:131], v[128:129] offset:256
	s_nop 0
	flat_load_dwordx4 v[140:143], v[132:133]
	s_nop 0
	flat_load_dwordx4 v[132:135], v[132:133] offset:256
	v_lshl_add_u64 v[232:233], s[14:15], 0, v[232:233]
	v_lshl_add_u64 v[230:231], v[232:233], 0, v[230:231]
	s_waitcnt vmcnt(0) lgkmcnt(0)
	v_lshlrev_b32_e32 v193, 16, v188
	v_and_b32_e32 v188, 0xffff0000, v188
	v_lshlrev_b32_e32 v239, 16, v191
	v_and_b32_e32 v191, 0xffff0000, v191
	v_add_f32_e32 v125, v125, v188
	v_lshlrev_b32_e32 v232, 16, v189
	v_add_f32_e32 v124, v124, v193
	v_add_f32_e32 v123, v123, v191
	v_mul_f32_e32 v191, v125, v125
	v_and_b32_e32 v189, 0xffff0000, v189
	v_add_f32_e32 v126, v126, v232
	v_fmac_f32_e32 v191, v124, v124
	v_lshlrev_b32_e32 v233, 16, v190
	v_add_f32_e32 v127, v127, v189
	v_fmac_f32_e32 v191, v126, v126
	v_and_b32_e32 v190, 0xffff0000, v190
	v_add_f32_e32 v188, v120, v233
	v_fmac_f32_e32 v191, v127, v127
	v_add_f32_e32 v189, v121, v190
	v_fmac_f32_e32 v191, v188, v188
	v_add_f32_e32 v190, v122, v239
	v_fmac_f32_e32 v191, v189, v189
	v_fmac_f32_e32 v191, v190, v190
	v_cvt_pk_bf16_f32 v120, v124, v125
	v_fmac_f32_e32 v191, v123, v123
	v_cvt_pk_bf16_f32 v121, v126, v127
	v_cvt_pk_bf16_f32 v122, v188, v189
	v_cvt_pk_bf16_f32 v123, v190, v123
	flat_store_dwordx4 v[230:231], v[120:123]
	v_lshlrev_b32_e32 v124, 16, v186
	v_and_b32_e32 v125, 0xffff0000, v186
	v_lshlrev_b32_e32 v120, 16, v184
	v_and_b32_e32 v121, 0xffff0000, v184
	v_add_f32_e32 v116, v116, v120
	v_lshlrev_b32_e32 v122, 16, v185
	v_add_f32_e32 v117, v117, v121
	v_fmac_f32_e32 v191, v116, v116
	v_and_b32_e32 v123, 0xffff0000, v185
	v_add_f32_e32 v118, v118, v122
	v_fmac_f32_e32 v191, v117, v117
	v_add_f32_e32 v119, v119, v123
	v_fmac_f32_e32 v191, v118, v118
	v_add_f32_e32 v120, v112, v124
	v_fmac_f32_e32 v191, v119, v119
	v_lshlrev_b32_e32 v126, 16, v187
	v_add_f32_e32 v121, v113, v125
	v_fmac_f32_e32 v191, v120, v120
	v_and_b32_e32 v127, 0xffff0000, v187
	v_add_f32_e32 v122, v114, v126
	v_fmac_f32_e32 v191, v121, v121
	v_add_f32_e32 v115, v115, v127
	v_fmac_f32_e32 v191, v122, v122
	v_cvt_pk_bf16_f32 v112, v116, v117
	v_cvt_pk_bf16_f32 v113, v118, v119
	v_fmac_f32_e32 v191, v115, v115
	v_cvt_pk_bf16_f32 v114, v120, v121
	v_cvt_pk_bf16_f32 v115, v122, v115
	flat_store_dwordx4 v[230:231], v[112:115] offset:256
	s_nop 1
	v_and_b32_e32 v113, 64, v238
	v_xor_b32_e32 v112, 16, v238
	v_add_u32_e32 v113, 64, v113
	v_cmp_lt_i32_e32 vcc, v112, v113
	v_xor_b32_e32 v115, 32, v238
	s_nop 0
	v_cndmask_b32_e32 v112, v238, v112, vcc
	v_lshlrev_b32_e32 v112, 2, v112
	ds_bpermute_b32 v114, v112, v191
	v_cmp_lt_i32_e32 vcc, v115, v113
	s_waitcnt lgkmcnt(0)
	v_add_f32_e32 v114, v191, v114
	v_cndmask_b32_e32 v113, v238, v115, vcc
	v_lshlrev_b32_e32 v113, 2, v113
	ds_bpermute_b32 v115, v113, v114
	s_and_saveexec_b64 s[14:15], s[4:5]
	s_cbranch_execz .LBB0_122
	s_waitcnt lgkmcnt(0)
	v_add_f32_e32 v114, v114, v115
	v_mul_f32_e32 v114, 0x49800000, v114
	v_trunc_f32_e32 v114, v114
	v_mul_f32_e32 v115, 0x2f800000, v114
	v_floor_f32_e32 v115, v115
	v_fmac_f32_e32 v114, 0xcf800000, v115
	v_cvt_u32_f32_e32 v114, v114
	v_cvt_u32_f32_e32 v115, v115
	v_readlane_b32 s16, v254, 37
	v_readlane_b32 s17, v254, 38
	s_nop 1
	v_lshl_add_u64 v[116:117], v[228:229], 3, s[16:17]
	flat_atomic_add_x2 v[116:117], v[114:115]

; template <class Epi>
; __device__ __forceinline__ void gemm_phase(LAS unsigned char* lds, const Gemm g, const StaticOrder& S, const Epi& E) {
;     ...
; #pragma unroll
;         for (int a = 0; a < 2; ++a)
; #pragma unroll
;             for (int b = 0; b < 2; ++b)
; #pragma unroll
;                 for (int m = 0; m < 4; ++m)
; #pragma unroll
;                     for (int n = 0; n < 2; ++n) acc[a][b][m][n] = (f32x4){0.f, 0.f, 0.f, 0.f};
;         cur = nxt; cA = nA; cB = nB; ++ui;
.LBB0_163:
	v_mov_b32_e32 v127, 0
	s_andn2_b64 vcc, exec, s[6:7]
	v_mov_b32_e32 v126, v127
	v_mov_b32_e32 v125, v127
	v_mov_b32_e32 v124, v127
	v_mov_b32_e32 v123, v127
	v_mov_b32_e32 v122, v127
	v_mov_b32_e32 v121, v127
	v_mov_b32_e32 v120, v127
	v_mov_b32_e32 v111, v127
	v_mov_b32_e32 v110, v127
	v_mov_b32_e32 v109, v127
	v_mov_b32_e32 v108, v127
	v_mov_b32_e32 v107, v127
	v_mov_b32_e32 v106, v127
	v_mov_b32_e32 v105, v127
	v_mov_b32_e32 v104, v127
	v_mov_b32_e32 v95, v127
	v_mov_b32_e32 v94, v127
	v_mov_b32_e32 v93, v127
	v_mov_b32_e32 v92, v127
	v_mov_b32_e32 v91, v127
	v_mov_b32_e32 v90, v127
	v_mov_b32_e32 v89, v127
	v_mov_b32_e32 v88, v127
	v_mov_b32_e32 v79, v127
	v_mov_b32_e32 v78, v127
	v_mov_b32_e32 v77, v127
	v_mov_b32_e32 v76, v127
	v_mov_b32_e32 v75, v127
	v_mov_b32_e32 v74, v127
	v_mov_b32_e32 v73, v127
	v_mov_b32_e32 v72, v127
	v_mov_b32_e32 v119, v127
	v_mov_b32_e32 v118, v127
	v_mov_b32_e32 v117, v127
	v_mov_b32_e32 v116, v127
	v_mov_b32_e32 v115, v127
	v_mov_b32_e32 v114, v127
	v_mov_b32_e32 v113, v127
	v_mov_b32_e32 v112, v127
	v_mov_b32_e32 v103, v127
	v_mov_b32_e32 v102, v127
	v_mov_b32_e32 v101, v127
	v_mov_b32_e32 v100, v127
	v_mov_b32_e32 v99, v127
	v_mov_b32_e32 v98, v127
	v_mov_b32_e32 v97, v127
	v_mov_b32_e32 v96, v127
	v_mov_b32_e32 v87, v127
	v_mov_b32_e32 v86, v127
	v_mov_b32_e32 v85, v127
	v_mov_b32_e32 v84, v127
	v_mov_b32_e32 v83, v127
	v_mov_b32_e32 v82, v127
	v_mov_b32_e32 v81, v127
	v_mov_b32_e32 v80, v127
	v_mov_b32_e32 v71, v127
	v_mov_b32_e32 v70, v127
	v_mov_b32_e32 v69, v127
	v_mov_b32_e32 v68, v127
	v_mov_b32_e32 v67, v127
	v_mov_b32_e32 v66, v127
	v_mov_b32_e32 v65, v127
	v_mov_b32_e32 v64, v127
	v_mov_b32_e32 v63, v127
	v_mov_b32_e32 v62, v127
	v_mov_b32_e32 v61, v127
	v_mov_b32_e32 v60, v127
	v_mov_b32_e32 v59, v127
	v_mov_b32_e32 v58, v127
	v_mov_b32_e32 v57, v127
	v_mov_b32_e32 v56, v127
	v_mov_b32_e32 v47, v127
	v_mov_b32_e32 v46, v127
	v_mov_b32_e32 v45, v127
	v_mov_b32_e32 v44, v127
	v_mov_b32_e32 v43, v127
	v_mov_b32_e32 v42, v127
	v_mov_b32_e32 v41, v127
	v_mov_b32_e32 v40, v127
	v_mov_b32_e32 v31, v127
	v_mov_b32_e32 v30, v127
	v_mov_b32_e32 v29, v127
	v_mov_b32_e32 v28, v127
	v_mov_b32_e32 v27, v127
	v_mov_b32_e32 v26, v127
	v_mov_b32_e32 v25, v127
	v_mov_b32_e32 v24, v127
	v_mov_b32_e32 v15, v127
	v_mov_b32_e32 v14, v127
	v_mov_b32_e32 v13, v127
	v_mov_b32_e32 v12, v127
	v_mov_b32_e32 v11, v127
	v_mov_b32_e32 v10, v127
	v_mov_b32_e32 v9, v127
	v_mov_b32_e32 v8, v127
	v_mov_b32_e32 v55, v127
	v_mov_b32_e32 v54, v127
	v_mov_b32_e32 v53, v127
	v_mov_b32_e32 v52, v127
	v_mov_b32_e32 v51, v127
	v_mov_b32_e32 v50, v127
	v_mov_b32_e32 v49, v127
	v_mov_b32_e32 v48, v127
	v_mov_b32_e32 v39, v127
	v_mov_b32_e32 v38, v127
	v_mov_b32_e32 v37, v127
	v_mov_b32_e32 v36, v127
	v_mov_b32_e32 v35, v127
	v_mov_b32_e32 v34, v127
	v_mov_b32_e32 v33, v127
	v_mov_b32_e32 v32, v127
	v_mov_b32_e32 v23, v127
	v_mov_b32_e32 v22, v127
	v_mov_b32_e32 v21, v127
	v_mov_b32_e32 v20, v127
	v_mov_b32_e32 v19, v127
	v_mov_b32_e32 v18, v127
	v_mov_b32_e32 v17, v127
	v_mov_b32_e32 v16, v127
	v_mov_b32_e32 v7, v127
	v_mov_b32_e32 v6, v127
	v_mov_b32_e32 v5, v127
	v_mov_b32_e32 v4, v127
	v_mov_b32_e32 v3, v127
	v_mov_b32_e32 v2, v127
	v_mov_b32_e32 v1, v127
	v_mov_b32_e32 v0, v127
	s_cbranch_vccnz .LBB0_166
	s_add_u32 s42, s18, 0x100
	s_addc_u32 s43, s19, 0
	s_add_u32 s16, s16, 0x80
	v_mov_b32_e32 v0, 0
	s_addc_u32 s17, s17, 0
	s_mov_b32 s18, 0
	v_mov_b32_e32 v1, v0
	v_mov_b32_e32 v2, v0
	v_mov_b32_e32 v3, v0
	v_mov_b32_e32 v4, v0
	v_mov_b32_e32 v5, v0
	v_mov_b32_e32 v6, v0
	v_mov_b32_e32 v7, v0
	v_mov_b32_e32 v16, v0
	v_mov_b32_e32 v17, v0
	v_mov_b32_e32 v18, v0
	v_mov_b32_e32 v19, v0
	v_mov_b32_e32 v20, v0
	v_mov_b32_e32 v21, v0
	v_mov_b32_e32 v22, v0
	v_mov_b32_e32 v23, v0
	v_mov_b32_e32 v32, v0
	v_mov_b32_e32 v33, v0
	v_mov_b32_e32 v34, v0
	v_mov_b32_e32 v35, v0
	v_mov_b32_e32 v36, v0
	v_mov_b32_e32 v37, v0
	v_mov_b32_e32 v38, v0
	v_mov_b32_e32 v39, v0
	v_mov_b32_e32 v48, v0
	v_mov_b32_e32 v49, v0
	v_mov_b32_e32 v50, v0
	v_mov_b32_e32 v51, v0
	v_mov_b32_e32 v52, v0
	v_mov_b32_e32 v53, v0
	v_mov_b32_e32 v54, v0
	v_mov_b32_e32 v55, v0
	v_mov_b32_e32 v8, v0
	v_mov_b32_e32 v9, v0
	v_mov_b32_e32 v10, v0
	v_mov_b32_e32 v11, v0
	v_mov_b32_e32 v12, v0
	v_mov_b32_e32 v13, v0
	v_mov_b32_e32 v14, v0
	v_mov_b32_e32 v15, v0
	v_mov_b32_e32 v24, v0
	v_mov_b32_e32 v25, v0
	v_mov_b32_e32 v26, v0
	v_mov_b32_e32 v27, v0
	v_mov_b32_e32 v28, v0
	v_mov_b32_e32 v29, v0
	v_mov_b32_e32 v30, v0
	v_mov_b32_e32 v31, v0
	v_mov_b32_e32 v40, v0
	v_mov_b32_e32 v41, v0
	v_mov_b32_e32 v42, v0
	v_mov_b32_e32 v43, v0
	v_mov_b32_e32 v44, v0
	v_mov_b32_e32 v45, v0
	v_mov_b32_e32 v46, v0
	v_mov_b32_e32 v47, v0
	v_mov_b32_e32 v56, v0
	v_mov_b32_e32 v57, v0
	v_mov_b32_e32 v58, v0
	v_mov_b32_e32 v59, v0
	v_mov_b32_e32 v60, v0
	v_mov_b32_e32 v61, v0
	v_mov_b32_e32 v62, v0
	v_mov_b32_e32 v63, v0
	v_mov_b32_e32 v64, v0
	v_mov_b32_e32 v65, v0
	v_mov_b32_e32 v66, v0
	v_mov_b32_e32 v67, v0
	v_mov_b32_e32 v68, v0
	v_mov_b32_e32 v69, v0
	v_mov_b32_e32 v70, v0
	v_mov_b32_e32 v71, v0
	v_mov_b32_e32 v80, v0
	v_mov_b32_e32 v81, v0
	v_mov_b32_e32 v82, v0
	v_mov_b32_e32 v83, v0
	v_mov_b32_e32 v84, v0
	v_mov_b32_e32 v85, v0
	v_mov_b32_e32 v86, v0
	v_mov_b32_e32 v87, v0
	v_mov_b32_e32 v96, v0
	v_mov_b32_e32 v97, v0
	v_mov_b32_e32 v98, v0
	v_mov_b32_e32 v99, v0
	v_mov_b32_e32 v100, v0
	v_mov_b32_e32 v101, v0
	v_mov_b32_e32 v102, v0
	v_mov_b32_e32 v103, v0
	v_mov_b32_e32 v112, v0
	v_mov_b32_e32 v113, v0
	v_mov_b32_e32 v114, v0
	v_mov_b32_e32 v115, v0
	v_mov_b32_e32 v116, v0
	v_mov_b32_e32 v117, v0
	v_mov_b32_e32 v118, v0
	v_mov_b32_e32 v119, v0
	v_mov_b32_e32 v72, v0
	v_mov_b32_e32 v73, v0
	v_mov_b32_e32 v74, v0
	v_mov_b32_e32 v75, v0
	v_mov_b32_e32 v76, v0
	v_mov_b32_e32 v77, v0
	v_mov_b32_e32 v78, v0
	v_mov_b32_e32 v79, v0
	v_mov_b32_e32 v88, v0
	v_mov_b32_e32 v89, v0
	v_mov_b32_e32 v90, v0
	v_mov_b32_e32 v91, v0
	v_mov_b32_e32 v92, v0
	v_mov_b32_e32 v93, v0
	v_mov_b32_e32 v94, v0
	v_mov_b32_e32 v95, v0
	v_mov_b32_e32 v104, v0
	v_mov_b32_e32 v105, v0
	v_mov_b32_e32 v106, v0
	v_mov_b32_e32 v107, v0
	v_mov_b32_e32 v108, v0
	v_mov_b32_e32 v109, v0
	v_mov_b32_e32 v110, v0
	v_mov_b32_e32 v111, v0
	v_mov_b32_e32 v120, v0
	v_mov_b32_e32 v121, v0
	v_mov_b32_e32 v122, v0
	v_mov_b32_e32 v123, v0
	v_mov_b32_e32 v124, v0
	v_mov_b32_e32 v125, v0
	v_mov_b32_e32 v126, v0
	v_mov_b32_e32 v127, v0
	s_mov_b64 s[48:49], 0x80
	v_readfirstlane_b32 s90, v192
	s_lshr_b32 s90, s90, 8
	s_cmp_eq_u32 s90, 1
	s_cbranch_scc0 .Lprio_skip_1
	s_setprio 1
; #define PG8_STAGE(bufoff, gbase, voff) do { _Pragma("unroll") for (int _i = 0; _i < 2; ++_i) \
;         __builtin_amdgcn_global_load_lds((const unsigned*)((const char*)(gbase) + (voff)[_i]), (LAS unsigned*)(lds + (bufoff) + ldsw + _i * 8192), 16, 0, 0); } while (0)
; #define PG8_LDA(dst, b, h) do { _Pragma("unroll") for (int m = 0; m < 4; ++m) _Pragma("unroll") for (int k = 0; k < 2; ++k) dst[m][k] = *(const LAS bf16x8*)(lds + PG8_SA(b, h) + aoff + m * 2048 + k * 1024); } while (0)
; #define PG8_LDB(dst, b, h) do { _Pragma("unroll") for (int n = 0; n < 2; ++n) _Pragma("unroll") for (int k = 0; k < 2; ++k) dst[n][k] = *(const LAS bf16x8*)(lds + PG8_SB(b, h) + boff + n * 2048 + k * 1024); } while (0)
; #define PG8_MMA(ai, bj, At, Bt) do { __builtin_amdgcn_s_setprio(1); _Pragma("unroll") for (int m = 0; m < 4; ++m) _Pragma("unroll") for (int n = 0; n < 2; ++n) _Pragma("unroll") for (int k = 0; k < 2; ++k) \
;         acc[ai][bj][m][n] = __builtin_amdgcn_mfma_f32_16x16x32_bf16(Bt[n][k], At[m][k], acc[ai][bj][m][n], 0, 0, 0); __builtin_amdgcn_s_setprio(0); } while (0)
; #define PG8_WAIT_L(n) asm volatile("s_waitcnt lgkmcnt(" #n ")" ::: "memory")
; #define PG8_BAR __builtin_amdgcn_s_barrier()
; #define PG8_SCHED __builtin_amdgcn_sched_barrier(0)
; template <class Epi>
; __device__ __forceinline__ void gemm_phase(LAS unsigned char* lds, const Gemm g, const StaticOrder& S, const Epi& E) {
;     ...
;         for (int t = 0; t < nt; t += 2) {
;             const bool last = (t == nt - 2);
;             const char* a1 = cA + (size_t)(t + 1) * kstep;
;             const char* a2 = last ? nA : cA + (size_t)(t + 2) * kstep; const char* b2 = last ? nB : cB + (size_t)(t + 2) * kstep;
;             const char* a3 = a2 + kstep; const char* b3 = b2 + kstep;
;             PG8_LDB(B0, 0, 0); PG8_SCHED; PG8_LDA(At, 0, 0); PG8_STAGE(PG8_SA(1, 1), a1 + hstep, voffA);
;             PG8_WAIT_L(8); PG8_BAR; PG8_WAIT_L(0); PG8_MMA(0, 0, At, B0); PG8_BAR; PG8_SCHED;
;             PG8_LDB(B1, 0, 1); PG8_STAGE(PG8_SB(0, 0), b2, voffB);
;             PG8_BAR; PG8_WAIT_L(0); PG8_MMA(0, 1, At, B1); PG8_BAR;
;             PG8_LDA(At, 0, 1); PG8_STAGE(PG8_SA(0, 0), a2, voffA);
;             PG8_BAR; PG8_WAIT_L(0); PG8_MMA(1, 0, At, B0); PG8_BAR; PG8_SCHED;
.Lprio_skip_1:
.LBB0_165:
	s_add_i32 s44, s18, 2
	s_add_u32 s20, s16, 0x80
	s_addc_u32 s19, s17, 0
	s_add_i32 s45, 0, 0x10000
	v_add_u32_e32 v142, s45, v146
	ds_read_b128 v[138:141], v142
	ds_read_b128 v[152:155], v142 offset:1024
	ds_read_b128 v[156:159], v142 offset:2048
	ds_read_b128 v[160:163], v142 offset:3072
	s_cmp_eq_u32 s35, s18
	s_cselect_b32 s18, s10, s20
	s_cselect_b32 s19, s11, s19
	s_cselect_b32 s21, s13, s43
	s_cselect_b32 s20, s12, s42
	v_lshl_add_u64 v[142:143], s[16:17], 0, v[136:137]
	s_add_i32 m0, s27, 0xc000
	ds_read_b128 v[164:167], v150
	ds_read_b128 v[168:171], v150 offset:1024
	ds_read_b128 v[172:175], v150 offset:2048
	ds_read_b128 v[176:179], v150 offset:3072
	ds_read_b128 v[180:183], v150 offset:4096
	ds_read_b128 v[184:187], v150 offset:5120
	ds_read_b128 v[188:191], v150 offset:6144
	ds_read_b128 v[202:205], v150 offset:7168
	global_load_lds_dwordx4 v[142:143], off
	v_lshl_add_u64 v[142:143], s[16:17], 0, v[134:135]
	s_add_i32 m0, s27, 0xe000
	s_nop 0
	global_load_lds_dwordx4 v[142:143], off
	s_waitcnt lgkmcnt(8)
	s_barrier
	s_waitcnt lgkmcnt(0)
	s_waitcnt lgkmcnt(0)
	v_mfma_f32_16x16x32_bf16 v[124:127], v[138:141], v[164:167], v[124:127]
	v_mfma_f32_16x16x32_bf16 v[120:123], v[156:159], v[164:167], v[120:123]
	v_mfma_f32_16x16x32_bf16 v[108:111], v[138:141], v[172:175], v[108:111]
	v_mfma_f32_16x16x32_bf16 v[104:107], v[156:159], v[172:175], v[104:107]
	v_mfma_f32_16x16x32_bf16 v[92:95], v[138:141], v[180:183], v[92:95]
	v_mfma_f32_16x16x32_bf16 v[88:91], v[156:159], v[180:183], v[88:91]
	v_mfma_f32_16x16x32_bf16 v[76:79], v[138:141], v[188:191], v[76:79]
	v_mfma_f32_16x16x32_bf16 v[72:75], v[156:159], v[188:191], v[72:75]
	v_mfma_f32_16x16x32_bf16 v[124:127], v[152:155], v[168:171], v[124:127]
	v_mfma_f32_16x16x32_bf16 v[120:123], v[160:163], v[168:171], v[120:123]
	v_mfma_f32_16x16x32_bf16 v[108:111], v[152:155], v[176:179], v[108:111]
	v_mfma_f32_16x16x32_bf16 v[104:107], v[160:163], v[176:179], v[104:107]
	v_mfma_f32_16x16x32_bf16 v[92:95], v[152:155], v[184:187], v[92:95]
	v_mfma_f32_16x16x32_bf16 v[88:91], v[160:163], v[184:187], v[88:91]
	v_mfma_f32_16x16x32_bf16 v[76:79], v[152:155], v[202:205], v[76:79]
	v_mfma_f32_16x16x32_bf16 v[72:75], v[160:163], v[202:205], v[72:75]
	s_barrier
	s_add_i32 s46, 0, 0x14000
	v_add_u32_e32 v142, s46, v146
	s_add_i32 s45, s45, s26
	ds_read_b128 v[206:209], v142
	ds_read_b128 v[210:213], v142 offset:1024
	ds_read_b128 v[214:217], v142 offset:2048
	ds_read_b128 v[218:221], v142 offset:3072
	v_lshl_add_u64 v[142:143], s[20:21], 0, v[194:195]
	s_mov_b32 m0, s45
	v_lshl_add_u64 v[222:223], s[20:21], 0, v[132:133]
	global_load_lds_dwordx4 v[142:143], off
	s_add_i32 m0, s45, 0x2000
	s_nop 0
	global_load_lds_dwordx4 v[222:223], off
	s_barrier
	s_waitcnt lgkmcnt(0)
	s_waitcnt lgkmcnt(0)
	v_mfma_f32_16x16x32_bf16 v[116:119], v[206:209], v[164:167], v[116:119]
	v_mfma_f32_16x16x32_bf16 v[112:115], v[214:217], v[164:167], v[112:115]
	v_mfma_f32_16x16x32_bf16 v[100:103], v[206:209], v[172:175], v[100:103]
	v_mfma_f32_16x16x32_bf16 v[96:99], v[214:217], v[172:175], v[96:99]
	v_mfma_f32_16x16x32_bf16 v[84:87], v[206:209], v[180:183], v[84:87]
	v_mfma_f32_16x16x32_bf16 v[80:83], v[214:217], v[180:183], v[80:83]
	v_mfma_f32_16x16x32_bf16 v[68:71], v[206:209], v[188:191], v[68:71]
	v_mfma_f32_16x16x32_bf16 v[64:67], v[214:217], v[188:191], v[64:67]
	v_mfma_f32_16x16x32_bf16 v[116:119], v[210:213], v[168:171], v[116:119]
	v_mfma_f32_16x16x32_bf16 v[112:115], v[218:221], v[168:171], v[112:115]
	v_mfma_f32_16x16x32_bf16 v[100:103], v[210:213], v[176:179], v[100:103]
	v_mfma_f32_16x16x32_bf16 v[96:99], v[218:221], v[176:179], v[96:99]
	v_mfma_f32_16x16x32_bf16 v[84:87], v[210:213], v[184:187], v[84:87]
	v_mfma_f32_16x16x32_bf16 v[80:83], v[218:221], v[184:187], v[80:83]
	v_mfma_f32_16x16x32_bf16 v[68:71], v[210:213], v[202:205], v[68:71]
	v_mfma_f32_16x16x32_bf16 v[64:67], v[218:221], v[202:205], v[64:67]
	s_mov_b32 m0, s27
	v_lshl_add_u64 v[224:225], s[18:19], 0, v[128:129]
	s_barrier
	ds_read_b128 v[164:167], v150 offset:16384
	ds_read_b128 v[168:171], v150 offset:17408
	ds_read_b128 v[172:175], v150 offset:18432
	ds_read_b128 v[176:179], v150 offset:19456
	ds_read_b128 v[180:183], v150 offset:20480
	ds_read_b128 v[184:187], v150 offset:21504
	ds_read_b128 v[188:191], v150 offset:22528
	ds_read_b128 v[202:205], v150 offset:23552
	global_load_lds_dwordx4 v[224:225], off
	v_lshl_add_u64 v[226:227], s[18:19], 0, v[130:131]
	s_mov_b32 m0, s28
	s_nop 0
	global_load_lds_dwordx4 v[226:227], off
	s_barrier
	s_waitcnt lgkmcnt(0)
	s_waitcnt lgkmcnt(0)
	v_mfma_f32_16x16x32_bf16 v[60:63], v[138:141], v[164:167], v[60:63]
	v_mfma_f32_16x16x32_bf16 v[56:59], v[156:159], v[164:167], v[56:59]
	v_mfma_f32_16x16x32_bf16 v[44:47], v[138:141], v[172:175], v[44:47]
	v_mfma_f32_16x16x32_bf16 v[40:43], v[156:159], v[172:175], v[40:43]
	v_mfma_f32_16x16x32_bf16 v[28:31], v[138:141], v[180:183], v[28:31]
	v_mfma_f32_16x16x32_bf16 v[24:27], v[156:159], v[180:183], v[24:27]
	v_mfma_f32_16x16x32_bf16 v[12:15], v[138:141], v[188:191], v[12:15]
	v_mfma_f32_16x16x32_bf16 v[8:11], v[156:159], v[188:191], v[8:11]
	v_mfma_f32_16x16x32_bf16 v[60:63], v[152:155], v[168:171], v[60:63]
	v_mfma_f32_16x16x32_bf16 v[56:59], v[160:163], v[168:171], v[56:59]
	v_mfma_f32_16x16x32_bf16 v[44:47], v[152:155], v[176:179], v[44:47]
	v_mfma_f32_16x16x32_bf16 v[40:43], v[160:163], v[176:179], v[40:43]
	v_mfma_f32_16x16x32_bf16 v[28:31], v[152:155], v[184:187], v[28:31]
	v_mfma_f32_16x16x32_bf16 v[24:27], v[160:163], v[184:187], v[24:27]
	v_mfma_f32_16x16x32_bf16 v[12:15], v[152:155], v[202:205], v[12:15]
	v_mfma_f32_16x16x32_bf16 v[8:11], v[160:163], v[202:205], v[8:11]
	s_barrier
; #define PG8_STAGE(bufoff, gbase, voff) do { _Pragma("unroll") for (int _i = 0; _i < 2; ++_i) \
;         __builtin_amdgcn_global_load_lds((const unsigned*)((const char*)(gbase) + (voff)[_i]), (LAS unsigned*)(lds + (bufoff) + ldsw + _i * 8192), 16, 0, 0); } while (0)
; #define PG8_LDA(dst, b, h) do { _Pragma("unroll") for (int m = 0; m < 4; ++m) _Pragma("unroll") for (int k = 0; k < 2; ++k) dst[m][k] = *(const LAS bf16x8*)(lds + PG8_SA(b, h) + aoff + m * 2048 + k * 1024); } while (0)
; #define PG8_LDB(dst, b, h) do { _Pragma("unroll") for (int n = 0; n < 2; ++n) _Pragma("unroll") for (int k = 0; k < 2; ++k) dst[n][k] = *(const LAS bf16x8*)(lds + PG8_SB(b, h) + boff + n * 2048 + k * 1024); } while (0)
; #define PG8_MMA(ai, bj, At, Bt) do { __builtin_amdgcn_s_setprio(1); _Pragma("unroll") for (int m = 0; m < 4; ++m) _Pragma("unroll") for (int n = 0; n < 2; ++n) _Pragma("unroll") for (int k = 0; k < 2; ++k) \
;         acc[ai][bj][m][n] = __builtin_amdgcn_mfma_f32_16x16x32_bf16(Bt[n][k], At[m][k], acc[ai][bj][m][n], 0, 0, 0); __builtin_amdgcn_s_setprio(0); } while (0)
; #define PG8_WAIT_V(n) asm volatile("s_waitcnt vmcnt(" #n ")" ::: "memory")
; #define PG8_WAIT_L(n) asm volatile("s_waitcnt lgkmcnt(" #n ")" ::: "memory")
; #define PG8_BAR __builtin_amdgcn_s_barrier()
; #define PG8_SCHED __builtin_amdgcn_sched_barrier(0)
; template <class Epi>
; __device__ __forceinline__ void gemm_phase(LAS unsigned char* lds, const Gemm g, const StaticOrder& S, const Epi& E) {
;     ...
;             PG8_STAGE(PG8_SB(0, 1), b2 + hstep, voffB);
;             PG8_WAIT_V(6); PG8_BAR; PG8_MMA(1, 1, At, B1); PG8_BAR;
;             PG8_LDB(B0, 1, 0); PG8_SCHED; PG8_LDA(At, 1, 0); PG8_STAGE(PG8_SA(0, 1), a2 + hstep, voffA);
;             PG8_WAIT_L(8); PG8_BAR; PG8_WAIT_L(0); PG8_MMA(0, 0, At, B0); PG8_BAR; PG8_SCHED;
;             PG8_LDB(B1, 1, 1); PG8_STAGE(PG8_SB(1, 0), b3, voffB);
;             PG8_BAR; PG8_WAIT_L(0); PG8_MMA(0, 1, At, B1); PG8_BAR;
;             PG8_LDA(At, 1, 1); PG8_STAGE(PG8_SA(1, 0), a3, voffA);
	s_add_u32 s20, s20, s2
	s_addc_u32 s21, s21, s3
	s_add_i32 s45, s46, s26
	v_lshl_add_u64 v[228:229], s[20:21], 0, v[194:195]
	s_mov_b32 m0, s45
	v_lshl_add_u64 v[230:231], s[20:21], 0, v[132:133]
	global_load_lds_dwordx4 v[228:229], off
	s_add_i32 m0, s45, 0x2000
	s_nop 0
	global_load_lds_dwordx4 v[230:231], off
	s_waitcnt vmcnt(6)
	s_barrier
	v_mfma_f32_16x16x32_bf16 v[52:55], v[206:209], v[164:167], v[52:55]
	v_mfma_f32_16x16x32_bf16 v[48:51], v[214:217], v[164:167], v[48:51]
	v_mfma_f32_16x16x32_bf16 v[36:39], v[206:209], v[172:175], v[36:39]
	v_mfma_f32_16x16x32_bf16 v[32:35], v[214:217], v[172:175], v[32:35]
	v_mfma_f32_16x16x32_bf16 v[20:23], v[206:209], v[180:183], v[20:23]
	v_mfma_f32_16x16x32_bf16 v[16:19], v[214:217], v[180:183], v[16:19]
	v_mfma_f32_16x16x32_bf16 v[4:7], v[206:209], v[188:191], v[4:7]
	v_mfma_f32_16x16x32_bf16 v[0:3], v[214:217], v[188:191], v[0:3]
	v_mfma_f32_16x16x32_bf16 v[52:55], v[210:213], v[168:171], v[52:55]
	v_mfma_f32_16x16x32_bf16 v[48:51], v[218:221], v[168:171], v[48:51]
	v_mfma_f32_16x16x32_bf16 v[36:39], v[210:213], v[176:179], v[36:39]
	v_mfma_f32_16x16x32_bf16 v[32:35], v[218:221], v[176:179], v[32:35]
	v_mfma_f32_16x16x32_bf16 v[20:23], v[210:213], v[184:187], v[20:23]
	v_mfma_f32_16x16x32_bf16 v[16:19], v[218:221], v[184:187], v[16:19]
	v_mfma_f32_16x16x32_bf16 v[4:7], v[210:213], v[202:205], v[4:7]
	v_mfma_f32_16x16x32_bf16 v[0:3], v[218:221], v[202:205], v[0:3]
	s_add_i32 s20, 0, 0x18000
	v_add_u32_e32 v151, s20, v146
	s_barrier
	ds_read_b128 v[138:141], v151
	ds_read_b128 v[152:155], v151 offset:1024
	ds_read_b128 v[156:159], v151 offset:2048
	ds_read_b128 v[160:163], v151 offset:3072
	s_add_u32 s18, s18, s2
	s_addc_u32 s19, s19, s3
	s_mov_b32 m0, s29
	v_lshl_add_u64 v[206:207], s[18:19], 0, v[128:129]
	ds_read_b128 v[164:167], v150 offset:32768
	ds_read_b128 v[168:171], v150 offset:33792
	ds_read_b128 v[172:175], v150 offset:34816
	ds_read_b128 v[176:179], v150 offset:35840
	ds_read_b128 v[180:183], v150 offset:36864
	ds_read_b128 v[184:187], v150 offset:37888
	ds_read_b128 v[188:191], v150 offset:38912
	ds_read_b128 v[202:205], v150 offset:39936
	global_load_lds_dwordx4 v[206:207], off
	v_lshl_add_u64 v[206:207], s[18:19], 0, v[130:131]
	s_mov_b32 m0, s30
	s_nop 0
	global_load_lds_dwordx4 v[206:207], off
	s_waitcnt lgkmcnt(8)
	s_barrier
	s_waitcnt lgkmcnt(0)
	s_waitcnt lgkmcnt(0)
	v_mfma_f32_16x16x32_bf16 v[124:127], v[138:141], v[164:167], v[124:127]
	v_mfma_f32_16x16x32_bf16 v[120:123], v[156:159], v[164:167], v[120:123]
	v_mfma_f32_16x16x32_bf16 v[108:111], v[138:141], v[172:175], v[108:111]
	v_mfma_f32_16x16x32_bf16 v[104:107], v[156:159], v[172:175], v[104:107]
	v_mfma_f32_16x16x32_bf16 v[92:95], v[138:141], v[180:183], v[92:95]
	v_mfma_f32_16x16x32_bf16 v[88:91], v[156:159], v[180:183], v[88:91]
	v_mfma_f32_16x16x32_bf16 v[76:79], v[138:141], v[188:191], v[76:79]
	v_mfma_f32_16x16x32_bf16 v[72:75], v[156:159], v[188:191], v[72:75]
	v_mfma_f32_16x16x32_bf16 v[124:127], v[152:155], v[168:171], v[124:127]
	v_mfma_f32_16x16x32_bf16 v[120:123], v[160:163], v[168:171], v[120:123]
	v_mfma_f32_16x16x32_bf16 v[108:111], v[152:155], v[176:179], v[108:111]
	v_mfma_f32_16x16x32_bf16 v[104:107], v[160:163], v[176:179], v[104:107]
	v_mfma_f32_16x16x32_bf16 v[92:95], v[152:155], v[184:187], v[92:95]
	v_mfma_f32_16x16x32_bf16 v[88:91], v[160:163], v[184:187], v[88:91]
	v_mfma_f32_16x16x32_bf16 v[76:79], v[152:155], v[202:205], v[76:79]
	v_mfma_f32_16x16x32_bf16 v[72:75], v[160:163], v[202:205], v[72:75]
	s_barrier
	s_add_i32 s18, 0, 0x1c000
	s_add_i32 s19, s20, s26
	v_add_u32_e32 v151, s18, v146
	v_lshl_add_u64 v[142:143], v[142:143], 0, s[48:49]
	s_mov_b32 m0, s19
	ds_read_b128 v[206:209], v151
	ds_read_b128 v[210:213], v151 offset:1024
	ds_read_b128 v[214:217], v151 offset:2048
	ds_read_b128 v[218:221], v151 offset:3072
	global_load_lds_dwordx4 v[142:143], off
	v_lshl_add_u64 v[142:143], v[222:223], 0, s[48:49]
	s_add_i32 m0, s19, 0x2000
	s_nop 0
	global_load_lds_dwordx4 v[142:143], off
	s_barrier
	s_waitcnt lgkmcnt(0)
	s_waitcnt lgkmcnt(0)
	v_mfma_f32_16x16x32_bf16 v[116:119], v[206:209], v[164:167], v[116:119]
	v_mfma_f32_16x16x32_bf16 v[112:115], v[214:217], v[164:167], v[112:115]
	v_mfma_f32_16x16x32_bf16 v[100:103], v[206:209], v[172:175], v[100:103]
	v_mfma_f32_16x16x32_bf16 v[96:99], v[214:217], v[172:175], v[96:99]
	v_mfma_f32_16x16x32_bf16 v[84:87], v[206:209], v[180:183], v[84:87]
	v_mfma_f32_16x16x32_bf16 v[80:83], v[214:217], v[180:183], v[80:83]
	v_mfma_f32_16x16x32_bf16 v[68:71], v[206:209], v[188:191], v[68:71]
	v_mfma_f32_16x16x32_bf16 v[64:67], v[214:217], v[188:191], v[64:67]
	v_mfma_f32_16x16x32_bf16 v[116:119], v[210:213], v[168:171], v[116:119]
	v_mfma_f32_16x16x32_bf16 v[112:115], v[218:221], v[168:171], v[112:115]
	v_mfma_f32_16x16x32_bf16 v[100:103], v[210:213], v[176:179], v[100:103]
	v_mfma_f32_16x16x32_bf16 v[96:99], v[218:221], v[176:179], v[96:99]
	v_mfma_f32_16x16x32_bf16 v[84:87], v[210:213], v[184:187], v[84:87]
	v_mfma_f32_16x16x32_bf16 v[80:83], v[218:221], v[184:187], v[80:83]
	v_mfma_f32_16x16x32_bf16 v[68:71], v[210:213], v[202:205], v[68:71]
	v_mfma_f32_16x16x32_bf16 v[64:67], v[218:221], v[202:205], v[64:67]
	s_mov_b32 m0, s31
	v_lshl_add_u64 v[142:143], v[224:225], 0, s[48:49]
	s_barrier
; #define LAS __attribute__((address_space(3)))
; #define PG8_STAGE(bufoff, gbase, voff) do { _Pragma("unroll") for (int _i = 0; _i < 2; ++_i) \
;         __builtin_amdgcn_global_load_lds((const unsigned*)((const char*)(gbase) + (voff)[_i]), (LAS unsigned*)(lds + (bufoff) + ldsw + _i * 8192), 16, 0, 0); } while (0)
; #define PG8_LDA(dst, b, h) do { _Pragma("unroll") for (int m = 0; m < 4; ++m) _Pragma("unroll") for (int k = 0; k < 2; ++k) dst[m][k] = *(const LAS bf16x8*)(lds + PG8_SA(b, h) + aoff + m * 2048 + k * 1024); } while (0)
; #define PG8_MMA(ai, bj, At, Bt) do { __builtin_amdgcn_s_setprio(1); _Pragma("unroll") for (int m = 0; m < 4; ++m) _Pragma("unroll") for (int n = 0; n < 2; ++n) _Pragma("unroll") for (int k = 0; k < 2; ++k) \
;         acc[ai][bj][m][n] = __builtin_amdgcn_mfma_f32_16x16x32_bf16(Bt[n][k], At[m][k], acc[ai][bj][m][n], 0, 0, 0); __builtin_amdgcn_s_setprio(0); } while (0)
; #define PG8_WAIT_V(n) asm volatile("s_waitcnt vmcnt(" #n ")" ::: "memory")
; #define PG8_WAIT_L(n) asm volatile("s_waitcnt lgkmcnt(" #n ")" ::: "memory")
; #define PG8_BAR __builtin_amdgcn_s_barrier()
; #define PG8_SCHED __builtin_amdgcn_sched_barrier(0)
; template <class Epi>
; __device__ __forceinline__ void gemm_phase(LAS unsigned char* lds, const Gemm g, const StaticOrder& S, const Epi& E) {
;     ...
;             PG8_LDA(At, 1, 1); PG8_STAGE(PG8_SA(1, 0), a3, voffA);
;             PG8_BAR; PG8_WAIT_L(0); PG8_MMA(1, 0, At, B0); PG8_BAR; PG8_SCHED;
;             PG8_STAGE(PG8_SB(1, 1), b3 + hstep, voffB);
;             PG8_WAIT_V(6); PG8_BAR; PG8_MMA(1, 1, At, B1); PG8_BAR;
;         }
;         E(acc, cur, wr, wc, fr, fq, lds, ui & 1, has_next ? nxt.pm : -1, tid);
;     __device__ __forceinline__ void stash(unsigned long long v, LAS unsigned char* lds, int par, int tid) const { if (tid < 256) *(LAS float*)(lds + 131072 + par * 1024 + tid * 4) = rsqrtf((float)v * (1.f / (1048576.f * DM)) + EPS_); }
;     __device__ __forceinline__ void operator()(const f32x4 (&acc)[2][2][4][2], const Unit& u, int wr, int wc, int fr, int fq, LAS unsigned char* lds, int par, int npm, int tid) const {
;         const int row0 = u.pm * BM + wr * 64 + fr, col0 = u.pn * BM + wc * 32 + 8 * fq;
;         unsigned long long nx = 0ull; if (npm >= 0) nx = prefetch(npm, tid);
	ds_read_b128 v[164:167], v150 offset:49152
	ds_read_b128 v[168:171], v150 offset:50176
	ds_read_b128 v[172:175], v150 offset:51200
	ds_read_b128 v[176:179], v150 offset:52224
	ds_read_b128 v[180:183], v150 offset:53248
	ds_read_b128 v[184:187], v150 offset:54272
	ds_read_b128 v[188:191], v150 offset:55296
	ds_read_b128 v[202:205], v150 offset:56320
	global_load_lds_dwordx4 v[142:143], off
	v_lshl_add_u64 v[142:143], v[226:227], 0, s[48:49]
	s_mov_b32 m0, s33
	s_nop 0
	global_load_lds_dwordx4 v[142:143], off
	s_barrier
	s_waitcnt lgkmcnt(0)
	s_waitcnt lgkmcnt(0)
	v_mfma_f32_16x16x32_bf16 v[60:63], v[138:141], v[164:167], v[60:63]
	v_mfma_f32_16x16x32_bf16 v[56:59], v[156:159], v[164:167], v[56:59]
	v_mfma_f32_16x16x32_bf16 v[44:47], v[138:141], v[172:175], v[44:47]
	v_mfma_f32_16x16x32_bf16 v[40:43], v[156:159], v[172:175], v[40:43]
	v_mfma_f32_16x16x32_bf16 v[28:31], v[138:141], v[180:183], v[28:31]
	v_mfma_f32_16x16x32_bf16 v[24:27], v[156:159], v[180:183], v[24:27]
	v_mfma_f32_16x16x32_bf16 v[12:15], v[138:141], v[188:191], v[12:15]
	v_mfma_f32_16x16x32_bf16 v[8:11], v[156:159], v[188:191], v[8:11]
	v_mfma_f32_16x16x32_bf16 v[60:63], v[152:155], v[168:171], v[60:63]
	v_mfma_f32_16x16x32_bf16 v[56:59], v[160:163], v[168:171], v[56:59]
	v_mfma_f32_16x16x32_bf16 v[44:47], v[152:155], v[176:179], v[44:47]
	v_mfma_f32_16x16x32_bf16 v[40:43], v[160:163], v[176:179], v[40:43]
	v_mfma_f32_16x16x32_bf16 v[28:31], v[152:155], v[184:187], v[28:31]
	v_mfma_f32_16x16x32_bf16 v[24:27], v[160:163], v[184:187], v[24:27]
	v_mfma_f32_16x16x32_bf16 v[12:15], v[152:155], v[202:205], v[12:15]
	v_mfma_f32_16x16x32_bf16 v[8:11], v[160:163], v[202:205], v[8:11]
	s_barrier
	s_add_i32 s18, s18, s26
	v_lshl_add_u64 v[138:139], v[228:229], 0, s[48:49]
	s_mov_b32 m0, s18
	s_nop 0
	global_load_lds_dwordx4 v[138:139], off
	v_lshl_add_u64 v[138:139], v[230:231], 0, s[48:49]
	s_add_i32 m0, s18, 0x2000
	s_nop 0
	global_load_lds_dwordx4 v[138:139], off
	s_waitcnt vmcnt(6)
	s_barrier
	v_mfma_f32_16x16x32_bf16 v[52:55], v[206:209], v[164:167], v[52:55]
	v_mfma_f32_16x16x32_bf16 v[48:51], v[214:217], v[164:167], v[48:51]
	v_mfma_f32_16x16x32_bf16 v[36:39], v[206:209], v[172:175], v[36:39]
	v_mfma_f32_16x16x32_bf16 v[32:35], v[214:217], v[172:175], v[32:35]
	v_mfma_f32_16x16x32_bf16 v[20:23], v[206:209], v[180:183], v[20:23]
	v_mfma_f32_16x16x32_bf16 v[16:19], v[214:217], v[180:183], v[16:19]
	v_mfma_f32_16x16x32_bf16 v[4:7], v[206:209], v[188:191], v[4:7]
	v_mfma_f32_16x16x32_bf16 v[0:3], v[214:217], v[188:191], v[0:3]
	v_mfma_f32_16x16x32_bf16 v[52:55], v[210:213], v[168:171], v[52:55]
	v_mfma_f32_16x16x32_bf16 v[48:51], v[218:221], v[168:171], v[48:51]
	v_mfma_f32_16x16x32_bf16 v[36:39], v[210:213], v[176:179], v[36:39]
	v_mfma_f32_16x16x32_bf16 v[32:35], v[218:221], v[176:179], v[32:35]
	v_mfma_f32_16x16x32_bf16 v[20:23], v[210:213], v[184:187], v[20:23]
	v_mfma_f32_16x16x32_bf16 v[16:19], v[218:221], v[184:187], v[16:19]
	v_mfma_f32_16x16x32_bf16 v[4:7], v[210:213], v[202:205], v[4:7]
	v_mfma_f32_16x16x32_bf16 v[0:3], v[218:221], v[202:205], v[0:3]
	s_add_u32 s42, s42, 0x100
	s_addc_u32 s43, s43, 0
	s_add_u32 s16, s16, 0x100
	s_addc_u32 s17, s17, 0
	s_cmp_ge_i32 s44, s34
	s_mov_b32 s18, s44
	s_barrier
	s_cbranch_scc0 .LBB0_165
.LBB0_166:
	s_setprio 0
	s_and_b64 s[14:15], s[14:15], exec
	s_cselect_b32 s18, s38, -1
	s_cmp_gt_i32 s18, -1
	s_cselect_b64 s[14:15], -1, 0
	s_and_b64 s[14:15], s[4:5], s[14:15]
	v_mov_b32_e32 v151, 0x358637bd
	s_and_saveexec_b64 s[16:17], s[14:15]
	s_cbranch_execz .LBB0_168
	v_lshl_add_u32 v138, s18, 8, v144
	v_readlane_b32 s18, v254, 39
	v_ashrrev_i32_e32 v139, 31, v138
	v_readlane_b32 s19, v254, 40
	s_nop 1
	v_lshl_add_u64 v[138:139], v[138:139], 3, s[18:19]
	flat_load_dwordx2 v[138:139], v[138:139]
	s_waitcnt vmcnt(0) lgkmcnt(0)
	v_ffbh_u32_e32 v140, v139
	v_min_u32_e32 v140, 32, v140
	v_lshlrev_b64 v[138:139], v140, v[138:139]
	v_min_u32_e32 v138, 1, v138
	v_or_b32_e32 v138, v139, v138
	v_cvt_f32_u32_e32 v138, v138
	v_sub_u32_e32 v139, 32, v140
	v_ldexp_f32 v138, v138, v139
	v_fmamk_f32 v151, v138, 0x30000000, v242

; #define LAS __attribute__((address_space(3)))
; __device__ __forceinline__ void unpack8(u32x4 w, float* f) { f[0] = bflo(w.x); f[1] = bfhi(w.x); f[2] = bflo(w.y); f[3] = bfhi(w.y); f[4] = bflo(w.z); f[5] = bfhi(w.z); f[6] = bflo(w.w); f[7] = bfhi(w.w); }
; __device__ __forceinline__ u32x4 pack8(const float* f) { u32x4 w; w.x = cvt_pk_bf16(f[0], f[1]); w.y = cvt_pk_bf16(f[2], f[3]); w.z = cvt_pk_bf16(f[4], f[5]); w.w = cvt_pk_bf16(f[6], f[7]); return w; }
;     __device__ __forceinline__ void operator()(const f32x4 (&acc)[2][2][4][2], const Unit& u, int wr, int wc, int fr, int fq, LAS unsigned char* lds, int par, int npm, int tid) const {
;         const int row0 = u.pm * BM + wr * 64 + fr, col0 = u.pn * BM + wc * 32 + 8 * fq;
;         u32x4 old[2][4][2];
; #pragma unroll
;         for (int ai = 0; ai < 2; ++ai)
; #pragma unroll
;             for (int m = 0; m < 4; ++m)
; #pragma unroll
;                 for (int bj = 0; bj < 2; ++bj) old[ai][m][bj] = *(const u32x4*)(Hb + (size_t)(row0 + ai * HALF + m * 16) * ldc + col0 + bj * HALF);
; #pragma unroll
;         for (int ai = 0; ai < 2; ++ai)
; #pragma unroll
;             for (int m = 0; m < 4; ++m) { const int row = row0 + ai * HALF + m * 16; bf16_t* hp = Hb + (size_t)row * ldc + col0;
;                 float part = 0.f;
; #pragma unroll
;                 for (int bj = 0; bj < 2; ++bj) { float o[8]; unpack8(old[ai][m][bj], o);
;                     const f32x4 a0 = acc[ai][bj][m][0], a1 = acc[ai][bj][m][1];
;                     float v[8] = {o[0] + a0[0], o[1] + a0[1], o[2] + a0[2], o[3] + a0[3], o[4] + a1[0], o[5] + a1[1], o[6] + a1[2], o[7] + a1[3]};
; #pragma unroll
;                     for (int k = 0; k < 8; ++k) part += v[k] * v[k];
;                     *(u32x4*)(hp + bj * HALF) = pack8(v); }
;                 part += __shfl_xor(part, 16); part += __shfl_xor(part, 32);
;                 if (fq == 0) atomicAdd(ssq + row, (unsigned long long)(part * 1048576.f)); }
.LBB0_201:
	s_setprio 0
	v_lshl_or_b32 v212, s38, 8, v246
	v_lshl_add_u32 v228, s37, 8, v201
	v_ashrrev_i32_e32 v213, 31, v212
	v_readlane_b32 s14, v254, 8
	v_lshlrev_b64 v[230:231], 1, v[212:213]
	v_readlane_b32 s15, v254, 9
	v_ashrrev_i32_e32 v229, 31, v228
	v_lshlrev_b64 v[232:233], 12, v[228:229]
	v_lshl_add_u64 v[132:133], s[14:15], 0, v[230:231]
	v_lshl_add_u64 v[128:129], v[132:133], 0, v[232:233]
	flat_load_dwordx4 v[188:191], v[128:129]
	flat_load_dwordx4 v[184:187], v[128:129] offset:256
	v_or_b32_e32 v226, 16, v228
	v_ashrrev_i32_e32 v227, 31, v226
	v_lshlrev_b64 v[128:129], 12, v[226:227]
	v_or_b32_e32 v224, 32, v228
	v_lshl_add_u64 v[128:129], v[132:133], 0, v[128:129]
	v_ashrrev_i32_e32 v225, 31, v224
	flat_load_dwordx4 v[180:183], v[128:129]
	flat_load_dwordx4 v[176:179], v[128:129] offset:256
	v_lshlrev_b64 v[128:129], 12, v[224:225]
	v_or_b32_e32 v222, 48, v228
	v_lshl_add_u64 v[128:129], v[132:133], 0, v[128:129]
	v_ashrrev_i32_e32 v223, 31, v222
	flat_load_dwordx4 v[172:175], v[128:129]
	flat_load_dwordx4 v[168:171], v[128:129] offset:256
	v_lshlrev_b64 v[128:129], 12, v[222:223]
	v_add_u32_e32 v220, 0x80, v228
	v_lshl_add_u64 v[128:129], v[132:133], 0, v[128:129]
	v_ashrrev_i32_e32 v221, 31, v220
	flat_load_dwordx4 v[164:167], v[128:129]
	flat_load_dwordx4 v[160:163], v[128:129] offset:256
	v_lshlrev_b64 v[128:129], 12, v[220:221]
	v_add_u32_e32 v218, 0x90, v228
	v_lshl_add_u64 v[128:129], v[132:133], 0, v[128:129]
	v_ashrrev_i32_e32 v219, 31, v218
	flat_load_dwordx4 v[156:159], v[128:129]
	flat_load_dwordx4 v[152:155], v[128:129] offset:256
	v_lshlrev_b64 v[128:129], 12, v[218:219]
	v_add_u32_e32 v216, 0xa0, v228
	v_add_u32_e32 v214, 0xb0, v228
	v_lshl_add_u64 v[128:129], v[132:133], 0, v[128:129]
	v_ashrrev_i32_e32 v217, 31, v216
	v_ashrrev_i32_e32 v215, 31, v214
	flat_load_dwordx4 v[148:151], v[128:129]
	flat_load_dwordx4 v[144:147], v[128:129] offset:256
	v_lshlrev_b64 v[128:129], 12, v[216:217]
	v_lshlrev_b64 v[134:135], 12, v[214:215]
	v_lshl_add_u64 v[128:129], v[132:133], 0, v[128:129]
	v_lshl_add_u64 v[132:133], v[132:133], 0, v[134:135]
	flat_load_dwordx4 v[136:139], v[128:129]
	s_nop 0
	flat_load_dwordx4 v[128:131], v[128:129] offset:256
	s_nop 0
	flat_load_dwordx4 v[140:143], v[132:133]
	s_nop 0
	flat_load_dwordx4 v[132:135], v[132:133] offset:256
	v_lshl_add_u64 v[232:233], s[14:15], 0, v[232:233]
	v_lshl_add_u64 v[230:231], v[232:233], 0, v[230:231]
	s_waitcnt vmcnt(0) lgkmcnt(0)
	v_lshlrev_b32_e32 v193, 16, v188
	v_and_b32_e32 v188, 0xffff0000, v188
	v_lshlrev_b32_e32 v239, 16, v191
	v_and_b32_e32 v191, 0xffff0000, v191
	v_add_f32_e32 v125, v125, v188
	v_lshlrev_b32_e32 v232, 16, v189
	v_add_f32_e32 v124, v124, v193
	v_add_f32_e32 v123, v123, v191
	v_mul_f32_e32 v191, v125, v125
	v_and_b32_e32 v189, 0xffff0000, v189
	v_add_f32_e32 v126, v126, v232
	v_fmac_f32_e32 v191, v124, v124
	v_lshlrev_b32_e32 v233, 16, v190
	v_add_f32_e32 v127, v127, v189
	v_fmac_f32_e32 v191, v126, v126
	v_and_b32_e32 v190, 0xffff0000, v190
	v_add_f32_e32 v188, v120, v233
	v_fmac_f32_e32 v191, v127, v127
	v_add_f32_e32 v189, v121, v190
	v_fmac_f32_e32 v191, v188, v188
	v_add_f32_e32 v190, v122, v239
	v_fmac_f32_e32 v191, v189, v189
	v_fmac_f32_e32 v191, v190, v190
	v_cvt_pk_bf16_f32 v120, v124, v125
	v_fmac_f32_e32 v191, v123, v123
	v_cvt_pk_bf16_f32 v121, v126, v127
	v_cvt_pk_bf16_f32 v122, v188, v189
	v_cvt_pk_bf16_f32 v123, v190, v123
	flat_store_dwordx4 v[230:231], v[120:123]
	v_lshlrev_b32_e32 v124, 16, v186
	v_and_b32_e32 v125, 0xffff0000, v186
	v_lshlrev_b32_e32 v120, 16, v184
	v_and_b32_e32 v121, 0xffff0000, v184
	v_add_f32_e32 v116, v116, v120
	v_lshlrev_b32_e32 v122, 16, v185
	v_add_f32_e32 v117, v117, v121
	v_fmac_f32_e32 v191, v116, v116
	v_and_b32_e32 v123, 0xffff0000, v185
	v_add_f32_e32 v118, v118, v122
	v_fmac_f32_e32 v191, v117, v117
	v_add_f32_e32 v119, v119, v123
	v_fmac_f32_e32 v191, v118, v118
	v_add_f32_e32 v120, v112, v124
	v_fmac_f32_e32 v191, v119, v119
	v_lshlrev_b32_e32 v126, 16, v187
	v_add_f32_e32 v121, v113, v125
	v_fmac_f32_e32 v191, v120, v120
	v_and_b32_e32 v127, 0xffff0000, v187
	v_add_f32_e32 v122, v114, v126
	v_fmac_f32_e32 v191, v121, v121
	v_add_f32_e32 v115, v115, v127
	v_fmac_f32_e32 v191, v122, v122
	v_cvt_pk_bf16_f32 v112, v116, v117
	v_cvt_pk_bf16_f32 v113, v118, v119
	v_fmac_f32_e32 v191, v115, v115
	v_cvt_pk_bf16_f32 v114, v120, v121
	v_cvt_pk_bf16_f32 v115, v122, v115
	flat_store_dwordx4 v[230:231], v[112:115] offset:256
	s_nop 1
	v_and_b32_e32 v113, 64, v238
	v_xor_b32_e32 v112, 16, v238
	v_add_u32_e32 v113, 64, v113
	v_cmp_lt_i32_e32 vcc, v112, v113
	v_xor_b32_e32 v115, 32, v238
	s_nop 0
	v_cndmask_b32_e32 v112, v238, v112, vcc
	v_lshlrev_b32_e32 v112, 2, v112
	ds_bpermute_b32 v114, v112, v191
	v_cmp_lt_i32_e32 vcc, v115, v113
	s_waitcnt lgkmcnt(0)
	v_add_f32_e32 v114, v191, v114
	v_cndmask_b32_e32 v113, v238, v115, vcc
	v_lshlrev_b32_e32 v113, 2, v113
	ds_bpermute_b32 v115, v113, v114
	s_and_saveexec_b64 s[14:15], s[4:5]
	s_cbranch_execz .LBB0_203
	s_waitcnt lgkmcnt(0)
	v_add_f32_e32 v114, v114, v115
	v_mul_f32_e32 v114, 0x49800000, v114
	v_trunc_f32_e32 v114, v114
	v_mul_f32_e32 v115, 0x2f800000, v114
	v_floor_f32_e32 v115, v115
	v_fmac_f32_e32 v114, 0xcf800000, v115
	v_cvt_u32_f32_e32 v114, v114
	v_cvt_u32_f32_e32 v115, v115
	v_readlane_b32 s16, v254, 39
	v_readlane_b32 s17, v254, 40
	s_nop 1
	v_lshl_add_u64 v[116:117], v[228:229], 3, s[16:17]
	flat_atomic_add_x2 v[116:117], v[114:115]

; template <class Epi>
; __device__ __forceinline__ void gemm_phase(LAS unsigned char* lds, const Gemm g, const StaticOrder& S, const Epi& E) {
;     ...
; #pragma unroll
;         for (int a = 0; a < 2; ++a)
; #pragma unroll
;             for (int b = 0; b < 2; ++b)
; #pragma unroll
;                 for (int m = 0; m < 4; ++m)
; #pragma unroll
;                     for (int n = 0; n < 2; ++n) acc[a][b][m][n] = (f32x4){0.f, 0.f, 0.f, 0.f};
;         cur = nxt; cA = nA; cB = nB; ++ui;
.LBB0_526:
	v_mov_b32_e32 v127, 0
	s_andn2_b64 vcc, exec, s[6:7]
	v_mov_b32_e32 v126, v127
	v_mov_b32_e32 v125, v127
	v_mov_b32_e32 v124, v127
	v_mov_b32_e32 v123, v127
	v_mov_b32_e32 v122, v127
	v_mov_b32_e32 v121, v127
	v_mov_b32_e32 v120, v127
	v_mov_b32_e32 v111, v127
	v_mov_b32_e32 v110, v127
	v_mov_b32_e32 v109, v127
	v_mov_b32_e32 v108, v127
	v_mov_b32_e32 v107, v127
	v_mov_b32_e32 v106, v127
	v_mov_b32_e32 v105, v127
	v_mov_b32_e32 v104, v127
	v_mov_b32_e32 v95, v127
	v_mov_b32_e32 v94, v127
	v_mov_b32_e32 v93, v127
	v_mov_b32_e32 v92, v127
	v_mov_b32_e32 v91, v127
	v_mov_b32_e32 v90, v127
	v_mov_b32_e32 v89, v127
	v_mov_b32_e32 v88, v127
	v_mov_b32_e32 v79, v127
	v_mov_b32_e32 v78, v127
	v_mov_b32_e32 v77, v127
	v_mov_b32_e32 v76, v127
	v_mov_b32_e32 v75, v127
	v_mov_b32_e32 v74, v127
	v_mov_b32_e32 v73, v127
	v_mov_b32_e32 v72, v127
	v_mov_b32_e32 v119, v127
	v_mov_b32_e32 v118, v127
	v_mov_b32_e32 v117, v127
	v_mov_b32_e32 v116, v127
	v_mov_b32_e32 v115, v127
	v_mov_b32_e32 v114, v127
	v_mov_b32_e32 v113, v127
	v_mov_b32_e32 v112, v127
	v_mov_b32_e32 v103, v127
	v_mov_b32_e32 v102, v127
	v_mov_b32_e32 v101, v127
	v_mov_b32_e32 v100, v127
	v_mov_b32_e32 v99, v127
	v_mov_b32_e32 v98, v127
	v_mov_b32_e32 v97, v127
	v_mov_b32_e32 v96, v127
	v_mov_b32_e32 v87, v127
	v_mov_b32_e32 v86, v127
	v_mov_b32_e32 v85, v127
	v_mov_b32_e32 v84, v127
	v_mov_b32_e32 v83, v127
	v_mov_b32_e32 v82, v127
	v_mov_b32_e32 v81, v127
	v_mov_b32_e32 v80, v127
	v_mov_b32_e32 v71, v127
	v_mov_b32_e32 v70, v127
	v_mov_b32_e32 v69, v127
	v_mov_b32_e32 v68, v127
	v_mov_b32_e32 v67, v127
	v_mov_b32_e32 v66, v127
	v_mov_b32_e32 v65, v127
	v_mov_b32_e32 v64, v127
	v_mov_b32_e32 v63, v127
	v_mov_b32_e32 v62, v127
	v_mov_b32_e32 v61, v127
	v_mov_b32_e32 v60, v127
	v_mov_b32_e32 v59, v127
	v_mov_b32_e32 v58, v127
	v_mov_b32_e32 v57, v127
	v_mov_b32_e32 v56, v127
	v_mov_b32_e32 v47, v127
	v_mov_b32_e32 v46, v127
	v_mov_b32_e32 v45, v127
	v_mov_b32_e32 v44, v127
	v_mov_b32_e32 v43, v127
	v_mov_b32_e32 v42, v127
	v_mov_b32_e32 v41, v127
	v_mov_b32_e32 v40, v127
	v_mov_b32_e32 v31, v127
	v_mov_b32_e32 v30, v127
	v_mov_b32_e32 v29, v127
	v_mov_b32_e32 v28, v127
	v_mov_b32_e32 v27, v127
	v_mov_b32_e32 v26, v127
	v_mov_b32_e32 v25, v127
	v_mov_b32_e32 v24, v127
	v_mov_b32_e32 v15, v127
	v_mov_b32_e32 v14, v127
	v_mov_b32_e32 v13, v127
	v_mov_b32_e32 v12, v127
	v_mov_b32_e32 v11, v127
	v_mov_b32_e32 v10, v127
	v_mov_b32_e32 v9, v127
	v_mov_b32_e32 v8, v127
	v_mov_b32_e32 v55, v127
	v_mov_b32_e32 v54, v127
	v_mov_b32_e32 v53, v127
	v_mov_b32_e32 v52, v127
	v_mov_b32_e32 v51, v127
	v_mov_b32_e32 v50, v127
	v_mov_b32_e32 v49, v127
	v_mov_b32_e32 v48, v127
	v_mov_b32_e32 v39, v127
	v_mov_b32_e32 v38, v127
	v_mov_b32_e32 v37, v127
	v_mov_b32_e32 v36, v127
	v_mov_b32_e32 v35, v127
	v_mov_b32_e32 v34, v127
	v_mov_b32_e32 v33, v127
	v_mov_b32_e32 v32, v127
	v_mov_b32_e32 v23, v127
	v_mov_b32_e32 v22, v127
	v_mov_b32_e32 v21, v127
	v_mov_b32_e32 v20, v127
	v_mov_b32_e32 v19, v127
	v_mov_b32_e32 v18, v127
	v_mov_b32_e32 v17, v127
	v_mov_b32_e32 v16, v127
	v_mov_b32_e32 v7, v127
	v_mov_b32_e32 v6, v127
	v_mov_b32_e32 v5, v127
	v_mov_b32_e32 v4, v127
	v_mov_b32_e32 v3, v127
	v_mov_b32_e32 v2, v127
	v_mov_b32_e32 v1, v127
	v_mov_b32_e32 v0, v127
	s_cbranch_vccnz .LBB0_529
	s_add_u32 s40, s18, 0x100
	s_addc_u32 s41, s19, 0
	s_add_u32 s16, s16, 0x80
	v_mov_b32_e32 v0, 0
	s_addc_u32 s17, s17, 0
	s_mov_b32 s18, 0
	v_mov_b32_e32 v1, v0
	v_mov_b32_e32 v2, v0
	v_mov_b32_e32 v3, v0
	v_mov_b32_e32 v4, v0
	v_mov_b32_e32 v5, v0
	v_mov_b32_e32 v6, v0
	v_mov_b32_e32 v7, v0
	v_mov_b32_e32 v16, v0
	v_mov_b32_e32 v17, v0
	v_mov_b32_e32 v18, v0
	v_mov_b32_e32 v19, v0
	v_mov_b32_e32 v20, v0
	v_mov_b32_e32 v21, v0
	v_mov_b32_e32 v22, v0
	v_mov_b32_e32 v23, v0
	v_mov_b32_e32 v32, v0
	v_mov_b32_e32 v33, v0
	v_mov_b32_e32 v34, v0
	v_mov_b32_e32 v35, v0
	v_mov_b32_e32 v36, v0
	v_mov_b32_e32 v37, v0
	v_mov_b32_e32 v38, v0
	v_mov_b32_e32 v39, v0
	v_mov_b32_e32 v48, v0
	v_mov_b32_e32 v49, v0
	v_mov_b32_e32 v50, v0
	v_mov_b32_e32 v51, v0
	v_mov_b32_e32 v52, v0
	v_mov_b32_e32 v53, v0
	v_mov_b32_e32 v54, v0
	v_mov_b32_e32 v55, v0
	v_mov_b32_e32 v8, v0
	v_mov_b32_e32 v9, v0
	v_mov_b32_e32 v10, v0
	v_mov_b32_e32 v11, v0
	v_mov_b32_e32 v12, v0
	v_mov_b32_e32 v13, v0
	v_mov_b32_e32 v14, v0
	v_mov_b32_e32 v15, v0
	v_mov_b32_e32 v24, v0
	v_mov_b32_e32 v25, v0
	v_mov_b32_e32 v26, v0
	v_mov_b32_e32 v27, v0
	v_mov_b32_e32 v28, v0
	v_mov_b32_e32 v29, v0
	v_mov_b32_e32 v30, v0
	v_mov_b32_e32 v31, v0
	v_mov_b32_e32 v40, v0
	v_mov_b32_e32 v41, v0
	v_mov_b32_e32 v42, v0
	v_mov_b32_e32 v43, v0
	v_mov_b32_e32 v44, v0
	v_mov_b32_e32 v45, v0
	v_mov_b32_e32 v46, v0
	v_mov_b32_e32 v47, v0
	v_mov_b32_e32 v56, v0
	v_mov_b32_e32 v57, v0
	v_mov_b32_e32 v58, v0
	v_mov_b32_e32 v59, v0
	v_mov_b32_e32 v60, v0
	v_mov_b32_e32 v61, v0
	v_mov_b32_e32 v62, v0
	v_mov_b32_e32 v63, v0
	v_mov_b32_e32 v64, v0
	v_mov_b32_e32 v65, v0
	v_mov_b32_e32 v66, v0
	v_mov_b32_e32 v67, v0
	v_mov_b32_e32 v68, v0
	v_mov_b32_e32 v69, v0
	v_mov_b32_e32 v70, v0
	v_mov_b32_e32 v71, v0
	v_mov_b32_e32 v80, v0
	v_mov_b32_e32 v81, v0
	v_mov_b32_e32 v82, v0
	v_mov_b32_e32 v83, v0
	v_mov_b32_e32 v84, v0
	v_mov_b32_e32 v85, v0
	v_mov_b32_e32 v86, v0
	v_mov_b32_e32 v87, v0
	v_mov_b32_e32 v96, v0
	v_mov_b32_e32 v97, v0
	v_mov_b32_e32 v98, v0
	v_mov_b32_e32 v99, v0
	v_mov_b32_e32 v100, v0
	v_mov_b32_e32 v101, v0
	v_mov_b32_e32 v102, v0
	v_mov_b32_e32 v103, v0
	v_mov_b32_e32 v112, v0
	v_mov_b32_e32 v113, v0
	v_mov_b32_e32 v114, v0
	v_mov_b32_e32 v115, v0
	v_mov_b32_e32 v116, v0
	v_mov_b32_e32 v117, v0
	v_mov_b32_e32 v118, v0
	v_mov_b32_e32 v119, v0
	v_mov_b32_e32 v72, v0
	v_mov_b32_e32 v73, v0
	v_mov_b32_e32 v74, v0
	v_mov_b32_e32 v75, v0
	v_mov_b32_e32 v76, v0
	v_mov_b32_e32 v77, v0
	v_mov_b32_e32 v78, v0
	v_mov_b32_e32 v79, v0
	v_mov_b32_e32 v88, v0
	v_mov_b32_e32 v89, v0
	v_mov_b32_e32 v90, v0
	v_mov_b32_e32 v91, v0
	v_mov_b32_e32 v92, v0
	v_mov_b32_e32 v93, v0
	v_mov_b32_e32 v94, v0
	v_mov_b32_e32 v95, v0
	v_mov_b32_e32 v104, v0
	v_mov_b32_e32 v105, v0
	v_mov_b32_e32 v106, v0
	v_mov_b32_e32 v107, v0
	v_mov_b32_e32 v108, v0
	v_mov_b32_e32 v109, v0
	v_mov_b32_e32 v110, v0
	v_mov_b32_e32 v111, v0
	v_mov_b32_e32 v120, v0
	v_mov_b32_e32 v121, v0
	v_mov_b32_e32 v122, v0
	v_mov_b32_e32 v123, v0
	v_mov_b32_e32 v124, v0
	v_mov_b32_e32 v125, v0
	v_mov_b32_e32 v126, v0
	v_mov_b32_e32 v127, v0
	s_mov_b64 s[46:47], 0x80
	v_readfirstlane_b32 s90, v192
	s_lshr_b32 s90, s90, 8
	s_cmp_eq_u32 s90, 1
	s_cbranch_scc0 .Lprio_skip_3
	s_setprio 1
; #define PG8_STAGE(bufoff, gbase, voff) do { _Pragma("unroll") for (int _i = 0; _i < 2; ++_i) \
;         __builtin_amdgcn_global_load_lds((const unsigned*)((const char*)(gbase) + (voff)[_i]), (LAS unsigned*)(lds + (bufoff) + ldsw + _i * 8192), 16, 0, 0); } while (0)
; #define PG8_LDA(dst, b, h) do { _Pragma("unroll") for (int m = 0; m < 4; ++m) _Pragma("unroll") for (int k = 0; k < 2; ++k) dst[m][k] = *(const LAS bf16x8*)(lds + PG8_SA(b, h) + aoff + m * 2048 + k * 1024); } while (0)
; #define PG8_LDB(dst, b, h) do { _Pragma("unroll") for (int n = 0; n < 2; ++n) _Pragma("unroll") for (int k = 0; k < 2; ++k) dst[n][k] = *(const LAS bf16x8*)(lds + PG8_SB(b, h) + boff + n * 2048 + k * 1024); } while (0)
; #define PG8_MMA(ai, bj, At, Bt) do { __builtin_amdgcn_s_setprio(1); _Pragma("unroll") for (int m = 0; m < 4; ++m) _Pragma("unroll") for (int n = 0; n < 2; ++n) _Pragma("unroll") for (int k = 0; k < 2; ++k) \
;         acc[ai][bj][m][n] = __builtin_amdgcn_mfma_f32_16x16x32_bf16(Bt[n][k], At[m][k], acc[ai][bj][m][n], 0, 0, 0); __builtin_amdgcn_s_setprio(0); } while (0)
; #define PG8_WAIT_L(n) asm volatile("s_waitcnt lgkmcnt(" #n ")" ::: "memory")
; #define PG8_BAR __builtin_amdgcn_s_barrier()
; #define PG8_SCHED __builtin_amdgcn_sched_barrier(0)
; template <class Epi>
; __device__ __forceinline__ void gemm_phase(LAS unsigned char* lds, const Gemm g, const StaticOrder& S, const Epi& E) {
;     ...
;         for (int t = 0; t < nt; t += 2) {
;             const bool last = (t == nt - 2);
;             const char* a1 = cA + (size_t)(t + 1) * kstep;
;             const char* a2 = last ? nA : cA + (size_t)(t + 2) * kstep; const char* b2 = last ? nB : cB + (size_t)(t + 2) * kstep;
;             const char* a3 = a2 + kstep; const char* b3 = b2 + kstep;
;             PG8_LDB(B0, 0, 0); PG8_SCHED; PG8_LDA(At, 0, 0); PG8_STAGE(PG8_SA(1, 1), a1 + hstep, voffA);
;             PG8_WAIT_L(8); PG8_BAR; PG8_WAIT_L(0); PG8_MMA(0, 0, At, B0); PG8_BAR; PG8_SCHED;
;             PG8_LDB(B1, 0, 1); PG8_STAGE(PG8_SB(0, 0), b2, voffB);
;             PG8_BAR; PG8_WAIT_L(0); PG8_MMA(0, 1, At, B1); PG8_BAR;
;             PG8_LDA(At, 0, 1); PG8_STAGE(PG8_SA(0, 0), a2, voffA);
;             PG8_BAR; PG8_WAIT_L(0); PG8_MMA(1, 0, At, B0); PG8_BAR; PG8_SCHED;
.Lprio_skip_3:
.LBB0_528:
	s_add_i32 s42, s18, 2
	s_add_u32 s20, s16, 0x80
	s_addc_u32 s19, s17, 0
	s_add_i32 s43, 0, 0x10000
	v_add_u32_e32 v149, s43, v144
	ds_read_b128 v[138:141], v149
	ds_read_b128 v[150:153], v149 offset:1024
	ds_read_b128 v[154:157], v149 offset:2048
	ds_read_b128 v[158:161], v149 offset:3072
	s_cmp_eq_u32 s33, s18
	s_cselect_b32 s18, s10, s20
	s_cselect_b32 s19, s11, s19
	s_cselect_b32 s21, s13, s41
	s_cselect_b32 s20, s12, s40
	v_lshl_add_u64 v[190:191], s[16:17], 0, v[136:137]
	s_add_i32 m0, s25, 0xc000
	ds_read_b128 v[162:165], v148
	ds_read_b128 v[166:169], v148 offset:1024
	ds_read_b128 v[170:173], v148 offset:2048
	ds_read_b128 v[174:177], v148 offset:3072
	ds_read_b128 v[178:181], v148 offset:4096
	ds_read_b128 v[182:185], v148 offset:5120
	ds_read_b128 v[186:189], v148 offset:6144
	ds_read_b128 v[202:205], v148 offset:7168
	global_load_lds_dwordx4 v[190:191], off
	v_lshl_add_u64 v[190:191], s[16:17], 0, v[134:135]
	s_add_i32 m0, s25, 0xe000
	s_nop 0
	global_load_lds_dwordx4 v[190:191], off
	s_waitcnt lgkmcnt(8)
	s_barrier
	s_waitcnt lgkmcnt(0)
	s_waitcnt lgkmcnt(0)
	v_mfma_f32_16x16x32_bf16 v[124:127], v[138:141], v[162:165], v[124:127]
	v_mfma_f32_16x16x32_bf16 v[120:123], v[154:157], v[162:165], v[120:123]
	v_mfma_f32_16x16x32_bf16 v[108:111], v[138:141], v[170:173], v[108:111]
	v_mfma_f32_16x16x32_bf16 v[104:107], v[154:157], v[170:173], v[104:107]
	v_mfma_f32_16x16x32_bf16 v[92:95], v[138:141], v[178:181], v[92:95]
	v_mfma_f32_16x16x32_bf16 v[88:91], v[154:157], v[178:181], v[88:91]
	v_mfma_f32_16x16x32_bf16 v[76:79], v[138:141], v[186:189], v[76:79]
	v_mfma_f32_16x16x32_bf16 v[72:75], v[154:157], v[186:189], v[72:75]
	v_mfma_f32_16x16x32_bf16 v[124:127], v[150:153], v[166:169], v[124:127]
	v_mfma_f32_16x16x32_bf16 v[120:123], v[158:161], v[166:169], v[120:123]
	v_mfma_f32_16x16x32_bf16 v[108:111], v[150:153], v[174:177], v[108:111]
	v_mfma_f32_16x16x32_bf16 v[104:107], v[158:161], v[174:177], v[104:107]
	v_mfma_f32_16x16x32_bf16 v[92:95], v[150:153], v[182:185], v[92:95]
	v_mfma_f32_16x16x32_bf16 v[88:91], v[158:161], v[182:185], v[88:91]
	v_mfma_f32_16x16x32_bf16 v[76:79], v[150:153], v[202:205], v[76:79]
	v_mfma_f32_16x16x32_bf16 v[72:75], v[158:161], v[202:205], v[72:75]
	s_barrier
	s_add_i32 s44, 0, 0x14000
	s_add_i32 s43, s43, s24
	v_add_u32_e32 v149, s44, v144
	v_lshl_add_u64 v[190:191], s[20:21], 0, v[194:195]
	s_mov_b32 m0, s43
	ds_read_b128 v[206:209], v149
	ds_read_b128 v[210:213], v149 offset:1024
	ds_read_b128 v[214:217], v149 offset:2048
	ds_read_b128 v[218:221], v149 offset:3072
	global_load_lds_dwordx4 v[190:191], off
	v_lshl_add_u64 v[222:223], s[20:21], 0, v[132:133]
	s_add_i32 m0, s43, 0x2000
	s_nop 0
	global_load_lds_dwordx4 v[222:223], off
	s_barrier
	s_waitcnt lgkmcnt(0)
	s_waitcnt lgkmcnt(0)
	v_mfma_f32_16x16x32_bf16 v[116:119], v[206:209], v[162:165], v[116:119]
	v_mfma_f32_16x16x32_bf16 v[112:115], v[214:217], v[162:165], v[112:115]
	v_mfma_f32_16x16x32_bf16 v[100:103], v[206:209], v[170:173], v[100:103]
	v_mfma_f32_16x16x32_bf16 v[96:99], v[214:217], v[170:173], v[96:99]
	v_mfma_f32_16x16x32_bf16 v[84:87], v[206:209], v[178:181], v[84:87]
	v_mfma_f32_16x16x32_bf16 v[80:83], v[214:217], v[178:181], v[80:83]
	v_mfma_f32_16x16x32_bf16 v[68:71], v[206:209], v[186:189], v[68:71]
	v_mfma_f32_16x16x32_bf16 v[64:67], v[214:217], v[186:189], v[64:67]
	v_mfma_f32_16x16x32_bf16 v[116:119], v[210:213], v[166:169], v[116:119]
	v_mfma_f32_16x16x32_bf16 v[112:115], v[218:221], v[166:169], v[112:115]
	v_mfma_f32_16x16x32_bf16 v[100:103], v[210:213], v[174:177], v[100:103]
	v_mfma_f32_16x16x32_bf16 v[96:99], v[218:221], v[174:177], v[96:99]
	v_mfma_f32_16x16x32_bf16 v[84:87], v[210:213], v[182:185], v[84:87]
	v_mfma_f32_16x16x32_bf16 v[80:83], v[218:221], v[182:185], v[80:83]
	v_mfma_f32_16x16x32_bf16 v[68:71], v[210:213], v[202:205], v[68:71]
	v_mfma_f32_16x16x32_bf16 v[64:67], v[218:221], v[202:205], v[64:67]
	s_mov_b32 m0, s25
	v_lshl_add_u64 v[224:225], s[18:19], 0, v[128:129]
	s_barrier
	ds_read_b128 v[162:165], v148 offset:16384
	ds_read_b128 v[166:169], v148 offset:17408
	ds_read_b128 v[170:173], v148 offset:18432
	ds_read_b128 v[174:177], v148 offset:19456
	ds_read_b128 v[178:181], v148 offset:20480
	ds_read_b128 v[182:185], v148 offset:21504
	ds_read_b128 v[186:189], v148 offset:22528
	ds_read_b128 v[202:205], v148 offset:23552
	global_load_lds_dwordx4 v[224:225], off
	v_lshl_add_u64 v[226:227], s[18:19], 0, v[130:131]
	s_mov_b32 m0, s26
	s_nop 0
	global_load_lds_dwordx4 v[226:227], off
	s_barrier
	s_waitcnt lgkmcnt(0)
	s_waitcnt lgkmcnt(0)
	v_mfma_f32_16x16x32_bf16 v[60:63], v[138:141], v[162:165], v[60:63]
	v_mfma_f32_16x16x32_bf16 v[56:59], v[154:157], v[162:165], v[56:59]
	v_mfma_f32_16x16x32_bf16 v[44:47], v[138:141], v[170:173], v[44:47]
	v_mfma_f32_16x16x32_bf16 v[40:43], v[154:157], v[170:173], v[40:43]
	v_mfma_f32_16x16x32_bf16 v[28:31], v[138:141], v[178:181], v[28:31]
	v_mfma_f32_16x16x32_bf16 v[24:27], v[154:157], v[178:181], v[24:27]
	v_mfma_f32_16x16x32_bf16 v[12:15], v[138:141], v[186:189], v[12:15]
	v_mfma_f32_16x16x32_bf16 v[8:11], v[154:157], v[186:189], v[8:11]
	v_mfma_f32_16x16x32_bf16 v[60:63], v[150:153], v[166:169], v[60:63]
	v_mfma_f32_16x16x32_bf16 v[56:59], v[158:161], v[166:169], v[56:59]
	v_mfma_f32_16x16x32_bf16 v[44:47], v[150:153], v[174:177], v[44:47]
	v_mfma_f32_16x16x32_bf16 v[40:43], v[158:161], v[174:177], v[40:43]
	v_mfma_f32_16x16x32_bf16 v[28:31], v[150:153], v[182:185], v[28:31]
	v_mfma_f32_16x16x32_bf16 v[24:27], v[158:161], v[182:185], v[24:27]
	v_mfma_f32_16x16x32_bf16 v[12:15], v[150:153], v[202:205], v[12:15]
	v_mfma_f32_16x16x32_bf16 v[8:11], v[158:161], v[202:205], v[8:11]
	s_barrier
; #define PG8_STAGE(bufoff, gbase, voff) do { _Pragma("unroll") for (int _i = 0; _i < 2; ++_i) \
;         __builtin_amdgcn_global_load_lds((const unsigned*)((const char*)(gbase) + (voff)[_i]), (LAS unsigned*)(lds + (bufoff) + ldsw + _i * 8192), 16, 0, 0); } while (0)
; #define PG8_LDA(dst, b, h) do { _Pragma("unroll") for (int m = 0; m < 4; ++m) _Pragma("unroll") for (int k = 0; k < 2; ++k) dst[m][k] = *(const LAS bf16x8*)(lds + PG8_SA(b, h) + aoff + m * 2048 + k * 1024); } while (0)
; #define PG8_LDB(dst, b, h) do { _Pragma("unroll") for (int n = 0; n < 2; ++n) _Pragma("unroll") for (int k = 0; k < 2; ++k) dst[n][k] = *(const LAS bf16x8*)(lds + PG8_SB(b, h) + boff + n * 2048 + k * 1024); } while (0)
; #define PG8_MMA(ai, bj, At, Bt) do { __builtin_amdgcn_s_setprio(1); _Pragma("unroll") for (int m = 0; m < 4; ++m) _Pragma("unroll") for (int n = 0; n < 2; ++n) _Pragma("unroll") for (int k = 0; k < 2; ++k) \
;         acc[ai][bj][m][n] = __builtin_amdgcn_mfma_f32_16x16x32_bf16(Bt[n][k], At[m][k], acc[ai][bj][m][n], 0, 0, 0); __builtin_amdgcn_s_setprio(0); } while (0)
; #define PG8_WAIT_V(n) asm volatile("s_waitcnt vmcnt(" #n ")" ::: "memory")
; #define PG8_WAIT_L(n) asm volatile("s_waitcnt lgkmcnt(" #n ")" ::: "memory")
; #define PG8_BAR __builtin_amdgcn_s_barrier()
; #define PG8_SCHED __builtin_amdgcn_sched_barrier(0)
; template <class Epi>
; __device__ __forceinline__ void gemm_phase(LAS unsigned char* lds, const Gemm g, const StaticOrder& S, const Epi& E) {
;     ...
;             PG8_STAGE(PG8_SB(0, 1), b2 + hstep, voffB);
;             PG8_WAIT_V(6); PG8_BAR; PG8_MMA(1, 1, At, B1); PG8_BAR;
;             PG8_LDB(B0, 1, 0); PG8_SCHED; PG8_LDA(At, 1, 0); PG8_STAGE(PG8_SA(0, 1), a2 + hstep, voffA);
;             PG8_WAIT_L(8); PG8_BAR; PG8_WAIT_L(0); PG8_MMA(0, 0, At, B0); PG8_BAR; PG8_SCHED;
;             PG8_LDB(B1, 1, 1); PG8_STAGE(PG8_SB(1, 0), b3, voffB);
;             PG8_BAR; PG8_WAIT_L(0); PG8_MMA(0, 1, At, B1); PG8_BAR;
;             PG8_LDA(At, 1, 1); PG8_STAGE(PG8_SA(1, 0), a3, voffA);
	s_add_u32 s20, s20, s2
	s_addc_u32 s21, s21, s3
	s_add_i32 s43, s44, s24
	v_lshl_add_u64 v[228:229], s[20:21], 0, v[194:195]
	s_mov_b32 m0, s43
	v_lshl_add_u64 v[230:231], s[20:21], 0, v[132:133]
	global_load_lds_dwordx4 v[228:229], off
	s_add_i32 m0, s43, 0x2000
	s_nop 0
	global_load_lds_dwordx4 v[230:231], off
	s_waitcnt vmcnt(6)
	s_barrier
	v_mfma_f32_16x16x32_bf16 v[52:55], v[206:209], v[162:165], v[52:55]
	v_mfma_f32_16x16x32_bf16 v[48:51], v[214:217], v[162:165], v[48:51]
	v_mfma_f32_16x16x32_bf16 v[36:39], v[206:209], v[170:173], v[36:39]
	v_mfma_f32_16x16x32_bf16 v[32:35], v[214:217], v[170:173], v[32:35]
	v_mfma_f32_16x16x32_bf16 v[20:23], v[206:209], v[178:181], v[20:23]
	v_mfma_f32_16x16x32_bf16 v[16:19], v[214:217], v[178:181], v[16:19]
	v_mfma_f32_16x16x32_bf16 v[4:7], v[206:209], v[186:189], v[4:7]
	v_mfma_f32_16x16x32_bf16 v[0:3], v[214:217], v[186:189], v[0:3]
	v_mfma_f32_16x16x32_bf16 v[52:55], v[210:213], v[166:169], v[52:55]
	v_mfma_f32_16x16x32_bf16 v[48:51], v[218:221], v[166:169], v[48:51]
	v_mfma_f32_16x16x32_bf16 v[36:39], v[210:213], v[174:177], v[36:39]
	v_mfma_f32_16x16x32_bf16 v[32:35], v[218:221], v[174:177], v[32:35]
	v_mfma_f32_16x16x32_bf16 v[20:23], v[210:213], v[182:185], v[20:23]
	v_mfma_f32_16x16x32_bf16 v[16:19], v[218:221], v[182:185], v[16:19]
	v_mfma_f32_16x16x32_bf16 v[4:7], v[210:213], v[202:205], v[4:7]
	v_mfma_f32_16x16x32_bf16 v[0:3], v[218:221], v[202:205], v[0:3]
	s_add_i32 s20, 0, 0x18000
	v_add_u32_e32 v149, s20, v144
	s_barrier
	ds_read_b128 v[138:141], v149
	ds_read_b128 v[150:153], v149 offset:1024
	ds_read_b128 v[154:157], v149 offset:2048
	ds_read_b128 v[158:161], v149 offset:3072
	s_add_u32 s18, s18, s2
	s_addc_u32 s19, s19, s3
	s_mov_b32 m0, s27
	v_lshl_add_u64 v[206:207], s[18:19], 0, v[128:129]
	ds_read_b128 v[162:165], v148 offset:32768
	ds_read_b128 v[166:169], v148 offset:33792
	ds_read_b128 v[170:173], v148 offset:34816
	ds_read_b128 v[174:177], v148 offset:35840
	ds_read_b128 v[178:181], v148 offset:36864
	ds_read_b128 v[182:185], v148 offset:37888
	ds_read_b128 v[186:189], v148 offset:38912
	ds_read_b128 v[202:205], v148 offset:39936
	global_load_lds_dwordx4 v[206:207], off
	v_lshl_add_u64 v[206:207], s[18:19], 0, v[130:131]
	s_mov_b32 m0, s28
	s_nop 0
	global_load_lds_dwordx4 v[206:207], off
	s_waitcnt lgkmcnt(8)
	s_barrier
	s_waitcnt lgkmcnt(0)
	s_waitcnt lgkmcnt(0)
	v_mfma_f32_16x16x32_bf16 v[124:127], v[138:141], v[162:165], v[124:127]
	v_mfma_f32_16x16x32_bf16 v[120:123], v[154:157], v[162:165], v[120:123]
	v_mfma_f32_16x16x32_bf16 v[108:111], v[138:141], v[170:173], v[108:111]
	v_mfma_f32_16x16x32_bf16 v[104:107], v[154:157], v[170:173], v[104:107]
	v_mfma_f32_16x16x32_bf16 v[92:95], v[138:141], v[178:181], v[92:95]
	v_mfma_f32_16x16x32_bf16 v[88:91], v[154:157], v[178:181], v[88:91]
	v_mfma_f32_16x16x32_bf16 v[76:79], v[138:141], v[186:189], v[76:79]
	v_mfma_f32_16x16x32_bf16 v[72:75], v[154:157], v[186:189], v[72:75]
	v_mfma_f32_16x16x32_bf16 v[124:127], v[150:153], v[166:169], v[124:127]
	v_mfma_f32_16x16x32_bf16 v[120:123], v[158:161], v[166:169], v[120:123]
	v_mfma_f32_16x16x32_bf16 v[108:111], v[150:153], v[174:177], v[108:111]
	v_mfma_f32_16x16x32_bf16 v[104:107], v[158:161], v[174:177], v[104:107]
	v_mfma_f32_16x16x32_bf16 v[92:95], v[150:153], v[182:185], v[92:95]
	v_mfma_f32_16x16x32_bf16 v[88:91], v[158:161], v[182:185], v[88:91]
	v_mfma_f32_16x16x32_bf16 v[76:79], v[150:153], v[202:205], v[76:79]
	v_mfma_f32_16x16x32_bf16 v[72:75], v[158:161], v[202:205], v[72:75]
	s_barrier
	s_add_i32 s18, 0, 0x1c000
	s_add_i32 s19, s20, s24
	v_add_u32_e32 v149, s18, v144
	v_lshl_add_u64 v[190:191], v[190:191], 0, s[46:47]
	s_mov_b32 m0, s19
	ds_read_b128 v[206:209], v149
	ds_read_b128 v[210:213], v149 offset:1024
	ds_read_b128 v[214:217], v149 offset:2048
	ds_read_b128 v[218:221], v149 offset:3072
	global_load_lds_dwordx4 v[190:191], off
	v_lshl_add_u64 v[190:191], v[222:223], 0, s[46:47]
	s_add_i32 m0, s19, 0x2000
	s_nop 0
	global_load_lds_dwordx4 v[190:191], off
	s_barrier
	s_waitcnt lgkmcnt(0)
	s_waitcnt lgkmcnt(0)
	v_mfma_f32_16x16x32_bf16 v[116:119], v[206:209], v[162:165], v[116:119]
	v_mfma_f32_16x16x32_bf16 v[112:115], v[214:217], v[162:165], v[112:115]
	v_mfma_f32_16x16x32_bf16 v[100:103], v[206:209], v[170:173], v[100:103]
	v_mfma_f32_16x16x32_bf16 v[96:99], v[214:217], v[170:173], v[96:99]
	v_mfma_f32_16x16x32_bf16 v[84:87], v[206:209], v[178:181], v[84:87]
	v_mfma_f32_16x16x32_bf16 v[80:83], v[214:217], v[178:181], v[80:83]
	v_mfma_f32_16x16x32_bf16 v[68:71], v[206:209], v[186:189], v[68:71]
	v_mfma_f32_16x16x32_bf16 v[64:67], v[214:217], v[186:189], v[64:67]
	v_mfma_f32_16x16x32_bf16 v[116:119], v[210:213], v[166:169], v[116:119]
	v_mfma_f32_16x16x32_bf16 v[112:115], v[218:221], v[166:169], v[112:115]
	v_mfma_f32_16x16x32_bf16 v[100:103], v[210:213], v[174:177], v[100:103]
	v_mfma_f32_16x16x32_bf16 v[96:99], v[218:221], v[174:177], v[96:99]
	v_mfma_f32_16x16x32_bf16 v[84:87], v[210:213], v[182:185], v[84:87]
	v_mfma_f32_16x16x32_bf16 v[80:83], v[218:221], v[182:185], v[80:83]
	v_mfma_f32_16x16x32_bf16 v[68:71], v[210:213], v[202:205], v[68:71]
	v_mfma_f32_16x16x32_bf16 v[64:67], v[218:221], v[202:205], v[64:67]
	s_mov_b32 m0, s29
	v_lshl_add_u64 v[190:191], v[224:225], 0, s[46:47]
	s_barrier
; #define LAS __attribute__((address_space(3)))
; #define PG8_STAGE(bufoff, gbase, voff) do { _Pragma("unroll") for (int _i = 0; _i < 2; ++_i) \
;         __builtin_amdgcn_global_load_lds((const unsigned*)((const char*)(gbase) + (voff)[_i]), (LAS unsigned*)(lds + (bufoff) + ldsw + _i * 8192), 16, 0, 0); } while (0)
; #define PG8_LDA(dst, b, h) do { _Pragma("unroll") for (int m = 0; m < 4; ++m) _Pragma("unroll") for (int k = 0; k < 2; ++k) dst[m][k] = *(const LAS bf16x8*)(lds + PG8_SA(b, h) + aoff + m * 2048 + k * 1024); } while (0)
; #define PG8_MMA(ai, bj, At, Bt) do { __builtin_amdgcn_s_setprio(1); _Pragma("unroll") for (int m = 0; m < 4; ++m) _Pragma("unroll") for (int n = 0; n < 2; ++n) _Pragma("unroll") for (int k = 0; k < 2; ++k) \
;         acc[ai][bj][m][n] = __builtin_amdgcn_mfma_f32_16x16x32_bf16(Bt[n][k], At[m][k], acc[ai][bj][m][n], 0, 0, 0); __builtin_amdgcn_s_setprio(0); } while (0)
; #define PG8_WAIT_V(n) asm volatile("s_waitcnt vmcnt(" #n ")" ::: "memory")
; #define PG8_WAIT_L(n) asm volatile("s_waitcnt lgkmcnt(" #n ")" ::: "memory")
; #define PG8_BAR __builtin_amdgcn_s_barrier()
; #define PG8_SCHED __builtin_amdgcn_sched_barrier(0)
; template <class Epi>
; __device__ __forceinline__ void gemm_phase(LAS unsigned char* lds, const Gemm g, const StaticOrder& S, const Epi& E) {
;     ...
;             PG8_LDA(At, 1, 1); PG8_STAGE(PG8_SA(1, 0), a3, voffA);
;             PG8_BAR; PG8_WAIT_L(0); PG8_MMA(1, 0, At, B0); PG8_BAR; PG8_SCHED;
;             PG8_STAGE(PG8_SB(1, 1), b3 + hstep, voffB);
;             PG8_WAIT_V(6); PG8_BAR; PG8_MMA(1, 1, At, B1); PG8_BAR;
;         }
;         E(acc, cur, wr, wc, fr, fq, lds, ui & 1, has_next ? nxt.pm : -1, tid);
;     __device__ __forceinline__ void stash(unsigned long long v, LAS unsigned char* lds, int par, int tid) const { if (tid < 256) *(LAS float*)(lds + 131072 + par * 1024 + tid * 4) = rsqrtf((float)v * (1.f / (1048576.f * DM)) + EPS_); }
;     __device__ __forceinline__ void operator()(const f32x4 (&acc)[2][2][4][2], const Unit& u, int wr, int wc, int fr, int fq, LAS unsigned char* lds, int par, int npm, int tid) const {
;         const int row0 = u.pm * BM + wr * 64 + fr, col0 = u.pn * BM + wc * 32 + 8 * fq;
;         unsigned long long nx = 0ull; if (npm >= 0) nx = prefetch(npm, tid);
	ds_read_b128 v[162:165], v148 offset:49152
	ds_read_b128 v[166:169], v148 offset:50176
	ds_read_b128 v[170:173], v148 offset:51200
	ds_read_b128 v[174:177], v148 offset:52224
	ds_read_b128 v[178:181], v148 offset:53248
	ds_read_b128 v[182:185], v148 offset:54272
	ds_read_b128 v[186:189], v148 offset:55296
	ds_read_b128 v[202:205], v148 offset:56320
	global_load_lds_dwordx4 v[190:191], off
	v_lshl_add_u64 v[190:191], v[226:227], 0, s[46:47]
	s_mov_b32 m0, s30
	s_nop 0
	global_load_lds_dwordx4 v[190:191], off
	s_barrier
	s_waitcnt lgkmcnt(0)
	s_waitcnt lgkmcnt(0)
	v_mfma_f32_16x16x32_bf16 v[60:63], v[138:141], v[162:165], v[60:63]
	v_mfma_f32_16x16x32_bf16 v[56:59], v[154:157], v[162:165], v[56:59]
	v_mfma_f32_16x16x32_bf16 v[44:47], v[138:141], v[170:173], v[44:47]
	v_mfma_f32_16x16x32_bf16 v[40:43], v[154:157], v[170:173], v[40:43]
	v_mfma_f32_16x16x32_bf16 v[28:31], v[138:141], v[178:181], v[28:31]
	v_mfma_f32_16x16x32_bf16 v[24:27], v[154:157], v[178:181], v[24:27]
	v_mfma_f32_16x16x32_bf16 v[12:15], v[138:141], v[186:189], v[12:15]
	v_mfma_f32_16x16x32_bf16 v[8:11], v[154:157], v[186:189], v[8:11]
	v_mfma_f32_16x16x32_bf16 v[60:63], v[150:153], v[166:169], v[60:63]
	v_mfma_f32_16x16x32_bf16 v[56:59], v[158:161], v[166:169], v[56:59]
	v_mfma_f32_16x16x32_bf16 v[44:47], v[150:153], v[174:177], v[44:47]
	v_mfma_f32_16x16x32_bf16 v[40:43], v[158:161], v[174:177], v[40:43]
	v_mfma_f32_16x16x32_bf16 v[28:31], v[150:153], v[182:185], v[28:31]
	v_mfma_f32_16x16x32_bf16 v[24:27], v[158:161], v[182:185], v[24:27]
	v_mfma_f32_16x16x32_bf16 v[12:15], v[150:153], v[202:205], v[12:15]
	v_mfma_f32_16x16x32_bf16 v[8:11], v[158:161], v[202:205], v[8:11]
	s_barrier
	s_add_i32 s18, s18, s24
	v_lshl_add_u64 v[138:139], v[228:229], 0, s[46:47]
	s_mov_b32 m0, s18
	s_nop 0
	global_load_lds_dwordx4 v[138:139], off
	v_lshl_add_u64 v[138:139], v[230:231], 0, s[46:47]
	s_add_i32 m0, s18, 0x2000
	s_nop 0
	global_load_lds_dwordx4 v[138:139], off
	s_waitcnt vmcnt(6)
	s_barrier
	v_mfma_f32_16x16x32_bf16 v[52:55], v[206:209], v[162:165], v[52:55]
	v_mfma_f32_16x16x32_bf16 v[48:51], v[214:217], v[162:165], v[48:51]
	v_mfma_f32_16x16x32_bf16 v[36:39], v[206:209], v[170:173], v[36:39]
	v_mfma_f32_16x16x32_bf16 v[32:35], v[214:217], v[170:173], v[32:35]
	v_mfma_f32_16x16x32_bf16 v[20:23], v[206:209], v[178:181], v[20:23]
	v_mfma_f32_16x16x32_bf16 v[16:19], v[214:217], v[178:181], v[16:19]
	v_mfma_f32_16x16x32_bf16 v[4:7], v[206:209], v[186:189], v[4:7]
	v_mfma_f32_16x16x32_bf16 v[0:3], v[214:217], v[186:189], v[0:3]
	v_mfma_f32_16x16x32_bf16 v[52:55], v[210:213], v[166:169], v[52:55]
	v_mfma_f32_16x16x32_bf16 v[48:51], v[218:221], v[166:169], v[48:51]
	v_mfma_f32_16x16x32_bf16 v[36:39], v[210:213], v[174:177], v[36:39]
	v_mfma_f32_16x16x32_bf16 v[32:35], v[218:221], v[174:177], v[32:35]
	v_mfma_f32_16x16x32_bf16 v[20:23], v[210:213], v[182:185], v[20:23]
	v_mfma_f32_16x16x32_bf16 v[16:19], v[218:221], v[182:185], v[16:19]
	v_mfma_f32_16x16x32_bf16 v[4:7], v[210:213], v[202:205], v[4:7]
	v_mfma_f32_16x16x32_bf16 v[0:3], v[218:221], v[202:205], v[0:3]
	s_add_u32 s40, s40, 0x100
	s_addc_u32 s41, s41, 0
	s_add_u32 s16, s16, 0x100
	s_addc_u32 s17, s17, 0
	s_cmp_ge_i32 s42, s31
	s_mov_b32 s18, s42
	s_barrier
	s_cbranch_scc0 .LBB0_528
.LBB0_529:
	s_setprio 0
	s_and_b64 s[14:15], s[14:15], exec
	s_cselect_b32 s18, s35, -1
	s_cmp_gt_i32 s18, -1
	s_cselect_b64 s[14:15], -1, 0
	s_and_b64 s[14:15], s[4:5], s[14:15]
	v_mov_b32_e32 v149, 0x358637bd
	s_and_saveexec_b64 s[16:17], s[14:15]
	s_cbranch_execz .LBB0_531
	v_lshl_add_u32 v138, s18, 8, v142
	v_readlane_b32 s18, v254, 37
	v_ashrrev_i32_e32 v139, 31, v138
	v_readlane_b32 s19, v254, 38
	s_nop 1
	v_lshl_add_u64 v[138:139], v[138:139], 3, s[18:19]
	flat_load_dwordx2 v[138:139], v[138:139]
	s_waitcnt vmcnt(0) lgkmcnt(0)
	v_ffbh_u32_e32 v140, v139
	v_min_u32_e32 v140, 32, v140
	v_lshlrev_b64 v[138:139], v140, v[138:139]
	v_min_u32_e32 v138, 1, v138
	v_or_b32_e32 v138, v139, v138
	v_cvt_f32_u32_e32 v138, v138
	v_sub_u32_e32 v139, 32, v140
	v_ldexp_f32 v138, v138, v139
	v_fmamk_f32 v149, v138, 0x30000000, v242
